# lean K-loop (padding-row MFMAs skipped) also for the pm==32 units of the gate-up and QKV GEMMs
# speedup vs baseline: 1.0059x; 1.0059x over previous
; #define PG8_STAGE(bufoff, gbase, voff) do { _Pragma("unroll") for (int _i = 0; _i < 2; ++_i) \
;         __builtin_amdgcn_global_load_lds((const unsigned*)((const char*)(gbase) + (voff)[_i]), (LAS unsigned*)(lds + (bufoff) + ldsw + _i * 8192), 16, 0, 0); } while (0)
; #define PG8_LDA(dst, b, h) do { _Pragma("unroll") for (int m = 0; m < 4; ++m) _Pragma("unroll") for (int k = 0; k < 2; ++k) dst[m][k] = *(const LAS bf16x8*)(lds + PG8_SA(b, h) + aoff + m * 2048 + k * 1024); } while (0)
; #define PG8_LDB(dst, b, h) do { _Pragma("unroll") for (int n = 0; n < 2; ++n) _Pragma("unroll") for (int k = 0; k < 2; ++k) dst[n][k] = *(const LAS bf16x8*)(lds + PG8_SB(b, h) + boff + n * 2048 + k * 1024); } while (0)
; #define PG8_MMA(ai, bj, At, Bt) do { __builtin_amdgcn_s_setprio(1); _Pragma("unroll") for (int m = 0; m < 4; ++m) _Pragma("unroll") for (int n = 0; n < 2; ++n) _Pragma("unroll") for (int k = 0; k < 2; ++k) \
;         acc[ai][bj][m][n] = __builtin_amdgcn_mfma_f32_16x16x32_bf16(Bt[n][k], At[m][k], acc[ai][bj][m][n], 0, 0, 0); __builtin_amdgcn_s_setprio(0); } while (0)
; #define PG8_WAIT_V(n) asm volatile("s_waitcnt vmcnt(" #n ")" ::: "memory")
; #define PG8_WAIT_L(n) asm volatile("s_waitcnt lgkmcnt(" #n ")" ::: "memory")
; #define PG8_BAR __builtin_amdgcn_s_barrier()
; #define PG8_SCHED __builtin_amdgcn_sched_barrier(0)
; template <class Epi>
; __device__ __forceinline__ void gemm_phase(LAS unsigned char* lds, const Sched& S, const Epi& E) {
;     ...
;     for (;;) {
;         const bool has_next = S.next(ui + 1, nxt);
;         const char* nA = has_next ? nxt.A : cA; const char* nB = has_next ? nxt.B : cB;
;         const int nt = cur.nt;
;         for (int t = 0; t < nt; t += 2) {
;             const bool last = (t == nt - 2);
;             const char* a1 = cA + (size_t)(t + 1) * kstep;
;             const char* a2 = last ? nA : cA + (size_t)(t + 2) * kstep; const char* b2 = last ? nB : cB + (size_t)(t + 2) * kstep;
;             const char* a3 = a2 + kstep; const char* b3 = b2 + kstep;
;             PG8_LDB(B0, 0, 0); PG8_LDB(B1, 0, 1); PG8_SCHED; PG8_LDA(At, 0, 0); PG8_STAGE(PG8_SA(1, 1), a1 + hstepA, voffA);
;             PG8_WAIT_V(8); PG8_WAIT_L(0); PG8_BAR; PG8_MMA(0, 0, At, B0); PG8_MMA(0, 1, At, B1); PG8_BAR; PG8_SCHED;
.LBB0_734:
	s_add_u32 s22, s22, 0x80080
	s_addc_u32 s23, s23, 0
	s_add_u32 s9, s24, 0x100
	v_mov_b32_e32 v2, 0
	s_addc_u32 s11, s25, 0
	s_mov_b32 s68, -2
	s_cmp_eq_u32 s16, 32
	s_cbranch_scc1 .Ltail_peel_qkv
	s_add_u32 s24, s22, 0xfff80080
	s_addc_u32 s25, s23, -1
	s_add_i32 s49, 0, 0x10000
	s_cmp_eq_u32 s68, 28
	s_cselect_b32 s27, s19, s25
	s_cselect_b32 s26, s18, s24
	v_add_u32_e32 v153, s49, v149
	s_cselect_b32 s25, s21, s11
	s_cselect_b32 s24, s20, s9
	s_add_i32 s69, 0, 0x14000
	ds_read_b128 v[140:143], v153
	ds_read_b128 v[144:147], v153 offset:1024
	ds_read_b128 v[154:157], v153 offset:2048
	ds_read_b128 v[158:161], v153 offset:3072
	v_add_u32_e32 v153, s69, v149
	ds_read_b128 v[162:165], v153
	ds_read_b128 v[176:179], v153 offset:1024
	ds_read_b128 v[180:183], v153 offset:2048
	ds_read_b128 v[184:187], v153 offset:3072
	v_lshl_add_u64 v[166:167], s[22:23], 0, v[136:137]
	s_add_i32 m0, s17, 0xc000
	ds_read_b128 v[188:191], v152
	ds_read_b128 v[192:195], v152 offset:1024
	ds_read_b128 v[196:199], v152 offset:2048
	ds_read_b128 v[222:225], v152 offset:3072
	ds_read_b128 v[226:229], v152 offset:4096
	ds_read_b128 v[230:233], v152 offset:5120
	ds_read_b128 v[234:237], v152 offset:6144
	ds_read_b128 v[238:241], v152 offset:7168
	global_load_lds_dwordx4 v[166:167], off
	v_lshl_add_u64 v[166:167], s[22:23], 0, v[138:139]
	s_add_i32 m0, s17, 0xe000
	s_nop 0
	global_load_lds_dwordx4 v[166:167], off
	s_waitcnt vmcnt(8)
	s_waitcnt lgkmcnt(0)
	s_barrier
	s_setprio 1
	s_waitcnt lgkmcnt(0)
	v_mfma_f32_16x16x32_bf16 v[126:129], v[140:143], v[188:191], 0
	v_mfma_f32_16x16x32_bf16 v[122:125], v[154:157], v[188:191], 0
	v_mfma_f32_16x16x32_bf16 v[114:117], v[140:143], v[196:199], 0
	v_mfma_f32_16x16x32_bf16 v[106:109], v[154:157], v[196:199], 0
	v_mfma_f32_16x16x32_bf16 v[98:101], v[140:143], v[226:229], 0
	v_mfma_f32_16x16x32_bf16 v[90:93], v[154:157], v[226:229], 0
	v_mfma_f32_16x16x32_bf16 v[82:85], v[140:143], v[234:237], 0
	v_mfma_f32_16x16x32_bf16 v[74:77], v[154:157], v[234:237], 0
	v_mfma_f32_16x16x32_bf16 v[126:129], v[144:147], v[192:195], v[126:129]
	v_mfma_f32_16x16x32_bf16 v[122:125], v[158:161], v[192:195], v[122:125]
	v_mfma_f32_16x16x32_bf16 v[114:117], v[144:147], v[222:225], v[114:117]
	v_mfma_f32_16x16x32_bf16 v[106:109], v[158:161], v[222:225], v[106:109]
	v_mfma_f32_16x16x32_bf16 v[98:101], v[144:147], v[230:233], v[98:101]
	v_mfma_f32_16x16x32_bf16 v[90:93], v[158:161], v[230:233], v[90:93]
	v_mfma_f32_16x16x32_bf16 v[82:85], v[144:147], v[238:241], v[82:85]
	v_mfma_f32_16x16x32_bf16 v[74:77], v[158:161], v[238:241], v[74:77]
	s_setprio 0
	s_setprio 1
	v_mfma_f32_16x16x32_bf16 v[118:121], v[162:165], v[188:191], 0
	v_mfma_f32_16x16x32_bf16 v[110:113], v[180:183], v[188:191], 0
	v_mfma_f32_16x16x32_bf16 v[102:105], v[162:165], v[196:199], 0
	v_mfma_f32_16x16x32_bf16 v[94:97], v[180:183], v[196:199], 0
	v_mfma_f32_16x16x32_bf16 v[86:89], v[162:165], v[226:229], 0
	v_mfma_f32_16x16x32_bf16 v[78:81], v[180:183], v[226:229], 0
	v_mfma_f32_16x16x32_bf16 v[70:73], v[162:165], v[234:237], 0
	v_mfma_f32_16x16x32_bf16 v[66:69], v[180:183], v[234:237], 0
	v_mfma_f32_16x16x32_bf16 v[118:121], v[176:179], v[192:195], v[118:121]
	v_mfma_f32_16x16x32_bf16 v[110:113], v[184:187], v[192:195], v[110:113]
	v_mfma_f32_16x16x32_bf16 v[102:105], v[176:179], v[222:225], v[102:105]
	v_mfma_f32_16x16x32_bf16 v[94:97], v[184:187], v[222:225], v[94:97]
	v_mfma_f32_16x16x32_bf16 v[86:89], v[176:179], v[230:233], v[86:89]
	v_mfma_f32_16x16x32_bf16 v[78:81], v[184:187], v[230:233], v[78:81]
	v_mfma_f32_16x16x32_bf16 v[70:73], v[176:179], v[238:241], v[70:73]
	v_mfma_f32_16x16x32_bf16 v[66:69], v[184:187], v[238:241], v[66:69]
	s_setprio 0
	s_barrier
	s_add_i32 s49, s49, s35
	v_lshl_add_u64 v[166:167], s[24:25], 0, v[168:169]
	s_mov_b32 m0, s49
	ds_read_b128 v[188:191], v152 offset:16384
	ds_read_b128 v[192:195], v152 offset:17408
	ds_read_b128 v[196:199], v152 offset:18432
	ds_read_b128 v[222:225], v152 offset:19456
	ds_read_b128 v[226:229], v152 offset:20480
	ds_read_b128 v[230:233], v152 offset:21504
	ds_read_b128 v[234:237], v152 offset:22528
	ds_read_b128 v[238:241], v152 offset:23552
	global_load_lds_dwordx4 v[166:167], off
	s_add_i32 m0, s49, 0x2000
	s_add_u32 s94, s24, 0x80000
	v_lshl_add_u64 v[200:201], s[24:25], 0, v[134:135]
	s_addc_u32 s95, s25, 0
	s_add_i32 s49, s69, s35
	global_load_lds_dwordx4 v[200:201], off
	v_lshl_add_u64 v[242:243], s[94:95], 0, v[168:169]
	s_mov_b32 m0, s49
	v_lshl_add_u64 v[244:245], s[26:27], 0, v[132:133]
	global_load_lds_dwordx4 v[242:243], off
	v_lshl_add_u64 v[242:243], s[94:95], 0, v[134:135]
	s_add_i32 m0, s49, 0x2000
	s_nop 0
	global_load_lds_dwordx4 v[242:243], off
	v_lshl_add_u64 v[242:243], s[26:27], 0, v[130:131]
	s_mov_b32 m0, s17
	s_nop 0
	global_load_lds_dwordx4 v[242:243], off
	s_mov_b32 m0, s36
	s_nop 0
	global_load_lds_dwordx4 v[244:245], off
	s_waitcnt vmcnt(8)
	s_waitcnt lgkmcnt(0)
	s_barrier
; #define PG8_STAGE(bufoff, gbase, voff) do { _Pragma("unroll") for (int _i = 0; _i < 2; ++_i) \
;         __builtin_amdgcn_global_load_lds((const unsigned*)((const char*)(gbase) + (voff)[_i]), (LAS unsigned*)(lds + (bufoff) + ldsw + _i * 8192), 16, 0, 0); } while (0)
; #define PG8_LDA(dst, b, h) do { _Pragma("unroll") for (int m = 0; m < 4; ++m) _Pragma("unroll") for (int k = 0; k < 2; ++k) dst[m][k] = *(const LAS bf16x8*)(lds + PG8_SA(b, h) + aoff + m * 2048 + k * 1024); } while (0)
; #define PG8_LDB(dst, b, h) do { _Pragma("unroll") for (int n = 0; n < 2; ++n) _Pragma("unroll") for (int k = 0; k < 2; ++k) dst[n][k] = *(const LAS bf16x8*)(lds + PG8_SB(b, h) + boff + n * 2048 + k * 1024); } while (0)
; #define PG8_MMA(ai, bj, At, Bt) do { __builtin_amdgcn_s_setprio(1); _Pragma("unroll") for (int m = 0; m < 4; ++m) _Pragma("unroll") for (int n = 0; n < 2; ++n) _Pragma("unroll") for (int k = 0; k < 2; ++k) \
;         acc[ai][bj][m][n] = __builtin_amdgcn_mfma_f32_16x16x32_bf16(Bt[n][k], At[m][k], acc[ai][bj][m][n], 0, 0, 0); __builtin_amdgcn_s_setprio(0); } while (0)
; #define PG8_WAIT_V(n) asm volatile("s_waitcnt vmcnt(" #n ")" ::: "memory")
; #define PG8_WAIT_L(n) asm volatile("s_waitcnt lgkmcnt(" #n ")" ::: "memory")
; #define PG8_BAR __builtin_amdgcn_s_barrier()
; #define PG8_SCHED __builtin_amdgcn_sched_barrier(0)
; template <class Epi>
; __device__ __forceinline__ void gemm_phase(LAS unsigned char* lds, const Sched& S, const Epi& E) {
;     ...
;             PG8_WAIT_V(8); PG8_WAIT_L(0); PG8_BAR; PG8_MMA(0, 0, At, B0); PG8_MMA(0, 1, At, B1); PG8_BAR; PG8_SCHED;
;             PG8_LDA(At, 0, 1); PG8_STAGE(PG8_SB(0, 0), b2, voffB); PG8_STAGE(PG8_SB(0, 1), b2 + hstepB, voffB); PG8_STAGE(PG8_SA(0, 0), a2, voffA);
;             PG8_WAIT_V(8); PG8_WAIT_L(0); PG8_BAR; PG8_MMA(1, 0, At, B0); PG8_MMA(1, 1, At, B1); PG8_BAR; PG8_SCHED;
;             PG8_LDB(B0, 1, 0); PG8_LDB(B1, 1, 1); PG8_SCHED; PG8_LDA(At, 1, 0); PG8_STAGE(PG8_SA(0, 1), a2 + hstepA, voffA);
;             PG8_WAIT_V(8); PG8_WAIT_L(0); PG8_BAR; PG8_MMA(0, 0, At, B0); PG8_MMA(0, 1, At, B1); PG8_BAR; PG8_SCHED;
	s_setprio 1
	s_waitcnt lgkmcnt(0)
	v_mfma_f32_16x16x32_bf16 v[62:65], v[140:143], v[188:191], 0
	v_mfma_f32_16x16x32_bf16 v[58:61], v[154:157], v[188:191], 0
	v_mfma_f32_16x16x32_bf16 v[50:53], v[140:143], v[196:199], 0
	v_mfma_f32_16x16x32_bf16 v[42:45], v[154:157], v[196:199], 0
	v_mfma_f32_16x16x32_bf16 v[34:37], v[140:143], v[226:229], 0
	v_mfma_f32_16x16x32_bf16 v[26:29], v[154:157], v[226:229], 0
	v_mfma_f32_16x16x32_bf16 v[18:21], v[140:143], v[234:237], 0
	v_mfma_f32_16x16x32_bf16 v[10:13], v[154:157], v[234:237], 0
	v_mfma_f32_16x16x32_bf16 v[62:65], v[144:147], v[192:195], v[62:65]
	v_mfma_f32_16x16x32_bf16 v[58:61], v[158:161], v[192:195], v[58:61]
	v_mfma_f32_16x16x32_bf16 v[50:53], v[144:147], v[222:225], v[50:53]
	v_mfma_f32_16x16x32_bf16 v[42:45], v[158:161], v[222:225], v[42:45]
	v_mfma_f32_16x16x32_bf16 v[34:37], v[144:147], v[230:233], v[34:37]
	v_mfma_f32_16x16x32_bf16 v[26:29], v[158:161], v[230:233], v[26:29]
	v_mfma_f32_16x16x32_bf16 v[18:21], v[144:147], v[238:241], v[18:21]
	v_mfma_f32_16x16x32_bf16 v[10:13], v[158:161], v[238:241], v[10:13]
	s_setprio 0
	s_setprio 1
	v_mfma_f32_16x16x32_bf16 v[54:57], v[162:165], v[188:191], 0
	v_mfma_f32_16x16x32_bf16 v[46:49], v[180:183], v[188:191], 0
	v_mfma_f32_16x16x32_bf16 v[38:41], v[162:165], v[196:199], 0
	v_mfma_f32_16x16x32_bf16 v[30:33], v[180:183], v[196:199], 0
	v_mfma_f32_16x16x32_bf16 v[22:25], v[162:165], v[226:229], 0
	v_mfma_f32_16x16x32_bf16 v[14:17], v[180:183], v[226:229], 0
	v_mfma_f32_16x16x32_bf16 v[6:9], v[162:165], v[234:237], 0
	v_mfma_f32_16x16x32_bf16 v[2:5], v[180:183], v[234:237], 0
	v_mfma_f32_16x16x32_bf16 v[54:57], v[176:179], v[192:195], v[54:57]
	v_mfma_f32_16x16x32_bf16 v[46:49], v[184:187], v[192:195], v[46:49]
	v_mfma_f32_16x16x32_bf16 v[38:41], v[176:179], v[222:225], v[38:41]
	v_mfma_f32_16x16x32_bf16 v[30:33], v[184:187], v[222:225], v[30:33]
	v_mfma_f32_16x16x32_bf16 v[22:25], v[176:179], v[230:233], v[22:25]
	v_mfma_f32_16x16x32_bf16 v[14:17], v[184:187], v[230:233], v[14:17]
	v_mfma_f32_16x16x32_bf16 v[6:9], v[176:179], v[238:241], v[6:9]
	v_mfma_f32_16x16x32_bf16 v[2:5], v[184:187], v[238:241], v[2:5]
	s_setprio 0
	s_barrier
	s_add_i32 s49, 0, 0x18000
	v_add_u32_e32 v153, s49, v149
	s_add_i32 s69, 0, 0x1c000
	ds_read_b128 v[140:143], v153
	ds_read_b128 v[144:147], v153 offset:1024
	ds_read_b128 v[154:157], v153 offset:2048
	ds_read_b128 v[158:161], v153 offset:3072
	v_add_u32_e32 v153, s69, v149
	ds_read_b128 v[162:165], v153
	ds_read_b128 v[176:179], v153 offset:1024
	ds_read_b128 v[180:183], v153 offset:2048
	ds_read_b128 v[184:187], v153 offset:3072
	s_add_u32 s26, s26, 0x80000
	s_addc_u32 s27, s27, 0
	s_mov_b32 m0, s37
	v_lshl_add_u64 v[246:247], s[26:27], 0, v[130:131]
	ds_read_b128 v[188:191], v152 offset:32768
	ds_read_b128 v[192:195], v152 offset:33792
	ds_read_b128 v[196:199], v152 offset:34816
	ds_read_b128 v[222:225], v152 offset:35840
	ds_read_b128 v[226:229], v152 offset:36864
	ds_read_b128 v[230:233], v152 offset:37888
	ds_read_b128 v[234:237], v152 offset:38912
	ds_read_b128 v[238:241], v152 offset:39936
	global_load_lds_dwordx4 v[246:247], off
	v_lshl_add_u64 v[246:247], s[26:27], 0, v[132:133]
	s_mov_b32 m0, s38
	s_nop 0
	global_load_lds_dwordx4 v[246:247], off
	s_waitcnt vmcnt(8)
	s_waitcnt lgkmcnt(0)
	s_barrier
	s_setprio 1
	s_waitcnt lgkmcnt(0)
	v_mfma_f32_16x16x32_bf16 v[126:129], v[140:143], v[188:191], v[126:129]
	v_mfma_f32_16x16x32_bf16 v[122:125], v[154:157], v[188:191], v[122:125]
	v_mfma_f32_16x16x32_bf16 v[114:117], v[140:143], v[196:199], v[114:117]
	v_mfma_f32_16x16x32_bf16 v[106:109], v[154:157], v[196:199], v[106:109]
	v_mfma_f32_16x16x32_bf16 v[98:101], v[140:143], v[226:229], v[98:101]
	v_mfma_f32_16x16x32_bf16 v[90:93], v[154:157], v[226:229], v[90:93]
	v_mfma_f32_16x16x32_bf16 v[82:85], v[140:143], v[234:237], v[82:85]
	v_mfma_f32_16x16x32_bf16 v[74:77], v[154:157], v[234:237], v[74:77]
	v_mfma_f32_16x16x32_bf16 v[126:129], v[144:147], v[192:195], v[126:129]
	v_mfma_f32_16x16x32_bf16 v[122:125], v[158:161], v[192:195], v[122:125]
	v_mfma_f32_16x16x32_bf16 v[114:117], v[144:147], v[222:225], v[114:117]
	v_mfma_f32_16x16x32_bf16 v[106:109], v[158:161], v[222:225], v[106:109]
	v_mfma_f32_16x16x32_bf16 v[98:101], v[144:147], v[230:233], v[98:101]
	v_mfma_f32_16x16x32_bf16 v[90:93], v[158:161], v[230:233], v[90:93]
	v_mfma_f32_16x16x32_bf16 v[82:85], v[144:147], v[238:241], v[82:85]
	v_mfma_f32_16x16x32_bf16 v[74:77], v[158:161], v[238:241], v[74:77]
	s_setprio 0
	s_setprio 1
	v_mfma_f32_16x16x32_bf16 v[118:121], v[162:165], v[188:191], v[118:121]
	v_mfma_f32_16x16x32_bf16 v[110:113], v[180:183], v[188:191], v[110:113]
	v_mfma_f32_16x16x32_bf16 v[102:105], v[162:165], v[196:199], v[102:105]
	v_mfma_f32_16x16x32_bf16 v[94:97], v[180:183], v[196:199], v[94:97]
	v_mfma_f32_16x16x32_bf16 v[86:89], v[162:165], v[226:229], v[86:89]
	v_mfma_f32_16x16x32_bf16 v[78:81], v[180:183], v[226:229], v[78:81]
	v_mfma_f32_16x16x32_bf16 v[70:73], v[162:165], v[234:237], v[70:73]
	v_mfma_f32_16x16x32_bf16 v[66:69], v[180:183], v[234:237], v[66:69]
	v_mfma_f32_16x16x32_bf16 v[118:121], v[176:179], v[192:195], v[118:121]
	v_mfma_f32_16x16x32_bf16 v[110:113], v[184:187], v[192:195], v[110:113]
	v_mfma_f32_16x16x32_bf16 v[102:105], v[176:179], v[222:225], v[102:105]
	v_mfma_f32_16x16x32_bf16 v[94:97], v[184:187], v[222:225], v[94:97]
	v_mfma_f32_16x16x32_bf16 v[86:89], v[176:179], v[230:233], v[86:89]
	v_mfma_f32_16x16x32_bf16 v[78:81], v[184:187], v[230:233], v[78:81]
	v_mfma_f32_16x16x32_bf16 v[70:73], v[176:179], v[238:241], v[70:73]
	v_mfma_f32_16x16x32_bf16 v[66:69], v[184:187], v[238:241], v[66:69]
	s_setprio 0
	s_barrier
; #define PG8_STAGE(bufoff, gbase, voff) do { _Pragma("unroll") for (int _i = 0; _i < 2; ++_i) \
;         __builtin_amdgcn_global_load_lds((const unsigned*)((const char*)(gbase) + (voff)[_i]), (LAS unsigned*)(lds + (bufoff) + ldsw + _i * 8192), 16, 0, 0); } while (0)
; #define PG8_LDA(dst, b, h) do { _Pragma("unroll") for (int m = 0; m < 4; ++m) _Pragma("unroll") for (int k = 0; k < 2; ++k) dst[m][k] = *(const LAS bf16x8*)(lds + PG8_SA(b, h) + aoff + m * 2048 + k * 1024); } while (0)
; #define PG8_LDB(dst, b, h) do { _Pragma("unroll") for (int n = 0; n < 2; ++n) _Pragma("unroll") for (int k = 0; k < 2; ++k) dst[n][k] = *(const LAS bf16x8*)(lds + PG8_SB(b, h) + boff + n * 2048 + k * 1024); } while (0)
; #define PG8_WAIT_V(n) asm volatile("s_waitcnt vmcnt(" #n ")" ::: "memory")
; #define PG8_WAIT_L(n) asm volatile("s_waitcnt lgkmcnt(" #n ")" ::: "memory")
; template <class Epi>
; __device__ __forceinline__ void gemm_phase(LAS unsigned char* lds, const Sched& S, const Epi& E) {
;     ...
;         for (int t = 0; t < nt; t += 2) {
;             const bool last = (t == nt - 2);
;             const char* a1 = cA + (size_t)(t + 1) * kstep;
;             const char* a2 = last ? nA : cA + (size_t)(t + 2) * kstep; const char* b2 = last ? nB : cB + (size_t)(t + 2) * kstep;
;             const char* a3 = a2 + kstep; const char* b3 = b2 + kstep;
;             PG8_LDB(B0, 0, 0); PG8_LDB(B1, 0, 1); PG8_SCHED; PG8_LDA(At, 0, 0); PG8_STAGE(PG8_SA(1, 1), a1 + hstepA, voffA);
;             PG8_WAIT_V(8); PG8_WAIT_L(0); PG8_BAR; PG8_MMA(0, 0, At, B0); PG8_MMA(0, 1, At, B1); PG8_BAR; PG8_SCHED;
;             PG8_LDA(At, 0, 1); PG8_STAGE(PG8_SB(0, 0), b2, voffB); PG8_STAGE(PG8_SB(0, 1), b2 + hstepB, voffB); PG8_STAGE(PG8_SA(0, 0), a2, voffA);
;             PG8_WAIT_V(8); PG8_WAIT_L(0); PG8_BAR; PG8_MMA(1, 0, At, B0); PG8_MMA(1, 1, At, B1); PG8_BAR; PG8_SCHED;
;             PG8_LDB(B0, 1, 0); PG8_LDB(B1, 1, 1); PG8_SCHED; PG8_LDA(At, 1, 0); PG8_STAGE(PG8_SA(0, 1), a2 + hstepA, voffA);
;             PG8_WAIT_V(8); PG8_WAIT_L(0); PG8_BAR; PG8_MMA(0, 0, At, B0); PG8_MMA(0, 1, At, B1); PG8_BAR; PG8_SCHED;
;             PG8_LDA(At, 1, 1); PG8_STAGE(PG8_SB(1, 0), b3, voffB); PG8_STAGE(PG8_SB(1, 1), b3 + hstepB, voffB); PG8_STAGE(PG8_SA(1, 0), a3, voffA);
;             PG8_WAIT_V(8); PG8_WAIT_L(0); PG8_BAR; PG8_MMA(1, 0, At, B0); PG8_MMA(1, 1, At, B1); PG8_BAR; PG8_SCHED;
;         }
	s_add_i32 s26, s49, s35
	v_lshl_add_u64 v[166:167], v[166:167], 0, s[0:1]
	s_mov_b32 m0, s26
	ds_read_b128 v[188:191], v152 offset:49152
	ds_read_b128 v[192:195], v152 offset:50176
	ds_read_b128 v[196:199], v152 offset:51200
	ds_read_b128 v[222:225], v152 offset:52224
	ds_read_b128 v[226:229], v152 offset:53248
	ds_read_b128 v[230:233], v152 offset:54272
	ds_read_b128 v[234:237], v152 offset:55296
	ds_read_b128 v[238:241], v152 offset:56320
	global_load_lds_dwordx4 v[166:167], off
	s_add_i32 m0, s26, 0x2000
	s_add_u32 s24, s24, 0x80080
	v_lshl_add_u64 v[166:167], v[200:201], 0, s[0:1]
	s_addc_u32 s25, s25, 0
	s_add_i32 s26, s69, s35
	global_load_lds_dwordx4 v[166:167], off
	v_lshl_add_u64 v[166:167], s[24:25], 0, v[168:169]
	s_mov_b32 m0, s26
	s_nop 0
	global_load_lds_dwordx4 v[166:167], off
	v_lshl_add_u64 v[166:167], s[24:25], 0, v[134:135]
	s_add_i32 m0, s26, 0x2000
	s_nop 0
	global_load_lds_dwordx4 v[166:167], off
	v_lshl_add_u64 v[166:167], v[242:243], 0, s[0:1]
	s_mov_b32 m0, s39
	s_nop 0
	global_load_lds_dwordx4 v[166:167], off
	v_lshl_add_u64 v[166:167], v[244:245], 0, s[0:1]
	s_mov_b32 m0, s59
	s_nop 0
	global_load_lds_dwordx4 v[166:167], off
	s_waitcnt vmcnt(8)
	s_waitcnt lgkmcnt(0)
	s_barrier
	s_setprio 1
	s_waitcnt lgkmcnt(0)
	v_mfma_f32_16x16x32_bf16 v[62:65], v[140:143], v[188:191], v[62:65]
	v_mfma_f32_16x16x32_bf16 v[58:61], v[154:157], v[188:191], v[58:61]
	v_mfma_f32_16x16x32_bf16 v[50:53], v[140:143], v[196:199], v[50:53]
	v_mfma_f32_16x16x32_bf16 v[42:45], v[154:157], v[196:199], v[42:45]
	v_mfma_f32_16x16x32_bf16 v[34:37], v[140:143], v[226:229], v[34:37]
	v_mfma_f32_16x16x32_bf16 v[26:29], v[154:157], v[226:229], v[26:29]
	v_mfma_f32_16x16x32_bf16 v[18:21], v[140:143], v[234:237], v[18:21]
	v_mfma_f32_16x16x32_bf16 v[10:13], v[154:157], v[234:237], v[10:13]
	v_mfma_f32_16x16x32_bf16 v[62:65], v[144:147], v[192:195], v[62:65]
	v_mfma_f32_16x16x32_bf16 v[58:61], v[158:161], v[192:195], v[58:61]
	v_mfma_f32_16x16x32_bf16 v[50:53], v[144:147], v[222:225], v[50:53]
	v_mfma_f32_16x16x32_bf16 v[42:45], v[158:161], v[222:225], v[42:45]
	v_mfma_f32_16x16x32_bf16 v[34:37], v[144:147], v[230:233], v[34:37]
	v_mfma_f32_16x16x32_bf16 v[26:29], v[158:161], v[230:233], v[26:29]
	v_mfma_f32_16x16x32_bf16 v[18:21], v[144:147], v[238:241], v[18:21]
	v_mfma_f32_16x16x32_bf16 v[10:13], v[158:161], v[238:241], v[10:13]
	s_setprio 0
	s_setprio 1
	v_mfma_f32_16x16x32_bf16 v[54:57], v[162:165], v[188:191], v[54:57]
	v_mfma_f32_16x16x32_bf16 v[46:49], v[180:183], v[188:191], v[46:49]
	v_mfma_f32_16x16x32_bf16 v[38:41], v[162:165], v[196:199], v[38:41]
	v_mfma_f32_16x16x32_bf16 v[30:33], v[180:183], v[196:199], v[30:33]
	v_mfma_f32_16x16x32_bf16 v[22:25], v[162:165], v[226:229], v[22:25]
	v_mfma_f32_16x16x32_bf16 v[14:17], v[180:183], v[226:229], v[14:17]
	v_mfma_f32_16x16x32_bf16 v[6:9], v[162:165], v[234:237], v[6:9]
	v_mfma_f32_16x16x32_bf16 v[2:5], v[180:183], v[234:237], v[2:5]
	v_mfma_f32_16x16x32_bf16 v[54:57], v[176:179], v[192:195], v[54:57]
	v_mfma_f32_16x16x32_bf16 v[46:49], v[184:187], v[192:195], v[46:49]
	v_mfma_f32_16x16x32_bf16 v[38:41], v[176:179], v[222:225], v[38:41]
	v_mfma_f32_16x16x32_bf16 v[30:33], v[184:187], v[222:225], v[30:33]
	v_mfma_f32_16x16x32_bf16 v[22:25], v[176:179], v[230:233], v[22:25]
	v_mfma_f32_16x16x32_bf16 v[14:17], v[184:187], v[230:233], v[14:17]
	v_mfma_f32_16x16x32_bf16 v[6:9], v[176:179], v[238:241], v[6:9]
	v_mfma_f32_16x16x32_bf16 v[2:5], v[184:187], v[238:241], v[2:5]
	s_setprio 0
	s_barrier
	s_add_i32 s68, s68, 2
	s_add_u32 s22, s22, 0x100
	s_addc_u32 s23, s23, 0
	s_add_u32 s9, s9, 0x100
	s_addc_u32 s11, s11, 0
	s_cmp_gt_u32 s68, 29
	s_cbranch_scc1 .Lpeel_exit_qkv
.LBB0_735:
	s_add_u32 s24, s22, 0xfff80080
	s_addc_u32 s25, s23, -1
	s_add_i32 s49, 0, 0x10000
	s_cmp_eq_u32 s68, 28
	s_cselect_b32 s27, s19, s25
	s_cselect_b32 s26, s18, s24
	v_add_u32_e32 v153, s49, v149
	s_cselect_b32 s25, s21, s11
	s_cselect_b32 s24, s20, s9
	s_add_i32 s69, 0, 0x14000
	ds_read_b128 v[140:143], v153
	ds_read_b128 v[144:147], v153 offset:1024
	ds_read_b128 v[154:157], v153 offset:2048
	ds_read_b128 v[158:161], v153 offset:3072
	v_add_u32_e32 v153, s69, v149
	ds_read_b128 v[162:165], v153
	ds_read_b128 v[176:179], v153 offset:1024
	ds_read_b128 v[180:183], v153 offset:2048
	ds_read_b128 v[184:187], v153 offset:3072
	v_lshl_add_u64 v[166:167], s[22:23], 0, v[136:137]
	s_add_i32 m0, s17, 0xc000
	ds_read_b128 v[188:191], v152
	ds_read_b128 v[192:195], v152 offset:1024
	ds_read_b128 v[196:199], v152 offset:2048
	ds_read_b128 v[222:225], v152 offset:3072
	ds_read_b128 v[226:229], v152 offset:4096
	ds_read_b128 v[230:233], v152 offset:5120
	ds_read_b128 v[234:237], v152 offset:6144
	ds_read_b128 v[238:241], v152 offset:7168
	global_load_lds_dwordx4 v[166:167], off
	v_lshl_add_u64 v[166:167], s[22:23], 0, v[138:139]
	s_add_i32 m0, s17, 0xe000
	s_nop 0
	global_load_lds_dwordx4 v[166:167], off
	s_waitcnt vmcnt(8)
	s_waitcnt lgkmcnt(0)
	s_barrier
; #define PG8_STAGE(bufoff, gbase, voff) do { _Pragma("unroll") for (int _i = 0; _i < 2; ++_i) \
;         __builtin_amdgcn_global_load_lds((const unsigned*)((const char*)(gbase) + (voff)[_i]), (LAS unsigned*)(lds + (bufoff) + ldsw + _i * 8192), 16, 0, 0); } while (0)
; #define PG8_LDA(dst, b, h) do { _Pragma("unroll") for (int m = 0; m < 4; ++m) _Pragma("unroll") for (int k = 0; k < 2; ++k) dst[m][k] = *(const LAS bf16x8*)(lds + PG8_SA(b, h) + aoff + m * 2048 + k * 1024); } while (0)
; #define PG8_MMA(ai, bj, At, Bt) do { __builtin_amdgcn_s_setprio(1); _Pragma("unroll") for (int m = 0; m < 4; ++m) _Pragma("unroll") for (int n = 0; n < 2; ++n) _Pragma("unroll") for (int k = 0; k < 2; ++k) \
;         acc[ai][bj][m][n] = __builtin_amdgcn_mfma_f32_16x16x32_bf16(Bt[n][k], At[m][k], acc[ai][bj][m][n], 0, 0, 0); __builtin_amdgcn_s_setprio(0); } while (0)
; #define PG8_WAIT_V(n) asm volatile("s_waitcnt vmcnt(" #n ")" ::: "memory")
; #define PG8_WAIT_L(n) asm volatile("s_waitcnt lgkmcnt(" #n ")" ::: "memory")
; #define PG8_BAR __builtin_amdgcn_s_barrier()
; #define PG8_SCHED __builtin_amdgcn_sched_barrier(0)
; template <class Epi>
; __device__ __forceinline__ void gemm_phase(LAS unsigned char* lds, const Sched& S, const Epi& E) {
;     ...
;             PG8_WAIT_V(8); PG8_WAIT_L(0); PG8_BAR; PG8_MMA(0, 0, At, B0); PG8_MMA(0, 1, At, B1); PG8_BAR; PG8_SCHED;
;             PG8_LDA(At, 0, 1); PG8_STAGE(PG8_SB(0, 0), b2, voffB); PG8_STAGE(PG8_SB(0, 1), b2 + hstepB, voffB); PG8_STAGE(PG8_SA(0, 0), a2, voffA);
;             PG8_WAIT_V(8); PG8_WAIT_L(0); PG8_BAR; PG8_MMA(1, 0, At, B0); PG8_MMA(1, 1, At, B1); PG8_BAR; PG8_SCHED;
	s_setprio 1
	s_waitcnt lgkmcnt(0)
	v_mfma_f32_16x16x32_bf16 v[126:129], v[140:143], v[188:191], v[126:129]
	v_mfma_f32_16x16x32_bf16 v[122:125], v[154:157], v[188:191], v[122:125]
	v_mfma_f32_16x16x32_bf16 v[114:117], v[140:143], v[196:199], v[114:117]
	v_mfma_f32_16x16x32_bf16 v[106:109], v[154:157], v[196:199], v[106:109]
	v_mfma_f32_16x16x32_bf16 v[98:101], v[140:143], v[226:229], v[98:101]
	v_mfma_f32_16x16x32_bf16 v[90:93], v[154:157], v[226:229], v[90:93]
	v_mfma_f32_16x16x32_bf16 v[82:85], v[140:143], v[234:237], v[82:85]
	v_mfma_f32_16x16x32_bf16 v[74:77], v[154:157], v[234:237], v[74:77]
	v_mfma_f32_16x16x32_bf16 v[126:129], v[144:147], v[192:195], v[126:129]
	v_mfma_f32_16x16x32_bf16 v[122:125], v[158:161], v[192:195], v[122:125]
	v_mfma_f32_16x16x32_bf16 v[114:117], v[144:147], v[222:225], v[114:117]
	v_mfma_f32_16x16x32_bf16 v[106:109], v[158:161], v[222:225], v[106:109]
	v_mfma_f32_16x16x32_bf16 v[98:101], v[144:147], v[230:233], v[98:101]
	v_mfma_f32_16x16x32_bf16 v[90:93], v[158:161], v[230:233], v[90:93]
	v_mfma_f32_16x16x32_bf16 v[82:85], v[144:147], v[238:241], v[82:85]
	v_mfma_f32_16x16x32_bf16 v[74:77], v[158:161], v[238:241], v[74:77]
	s_setprio 0
	s_setprio 1
	v_mfma_f32_16x16x32_bf16 v[118:121], v[162:165], v[188:191], v[118:121]
	v_mfma_f32_16x16x32_bf16 v[110:113], v[180:183], v[188:191], v[110:113]
	v_mfma_f32_16x16x32_bf16 v[102:105], v[162:165], v[196:199], v[102:105]
	v_mfma_f32_16x16x32_bf16 v[94:97], v[180:183], v[196:199], v[94:97]
	v_mfma_f32_16x16x32_bf16 v[86:89], v[162:165], v[226:229], v[86:89]
	v_mfma_f32_16x16x32_bf16 v[78:81], v[180:183], v[226:229], v[78:81]
	v_mfma_f32_16x16x32_bf16 v[70:73], v[162:165], v[234:237], v[70:73]
	v_mfma_f32_16x16x32_bf16 v[66:69], v[180:183], v[234:237], v[66:69]
	v_mfma_f32_16x16x32_bf16 v[118:121], v[176:179], v[192:195], v[118:121]
	v_mfma_f32_16x16x32_bf16 v[110:113], v[184:187], v[192:195], v[110:113]
	v_mfma_f32_16x16x32_bf16 v[102:105], v[176:179], v[222:225], v[102:105]
	v_mfma_f32_16x16x32_bf16 v[94:97], v[184:187], v[222:225], v[94:97]
	v_mfma_f32_16x16x32_bf16 v[86:89], v[176:179], v[230:233], v[86:89]
	v_mfma_f32_16x16x32_bf16 v[78:81], v[184:187], v[230:233], v[78:81]
	v_mfma_f32_16x16x32_bf16 v[70:73], v[176:179], v[238:241], v[70:73]
	v_mfma_f32_16x16x32_bf16 v[66:69], v[184:187], v[238:241], v[66:69]
	s_setprio 0
	s_barrier
	s_add_i32 s49, s49, s35
	v_lshl_add_u64 v[166:167], s[24:25], 0, v[168:169]
	s_mov_b32 m0, s49
	ds_read_b128 v[188:191], v152 offset:16384
	ds_read_b128 v[192:195], v152 offset:17408
	ds_read_b128 v[196:199], v152 offset:18432
	ds_read_b128 v[222:225], v152 offset:19456
	ds_read_b128 v[226:229], v152 offset:20480
	ds_read_b128 v[230:233], v152 offset:21504
	ds_read_b128 v[234:237], v152 offset:22528
	ds_read_b128 v[238:241], v152 offset:23552
	global_load_lds_dwordx4 v[166:167], off
	s_add_i32 m0, s49, 0x2000
	s_add_u32 s94, s24, 0x80000
	v_lshl_add_u64 v[200:201], s[24:25], 0, v[134:135]
	s_addc_u32 s95, s25, 0
	s_add_i32 s49, s69, s35
	global_load_lds_dwordx4 v[200:201], off
	v_lshl_add_u64 v[242:243], s[94:95], 0, v[168:169]
	s_mov_b32 m0, s49
	v_lshl_add_u64 v[244:245], s[26:27], 0, v[132:133]
	global_load_lds_dwordx4 v[242:243], off
	v_lshl_add_u64 v[242:243], s[94:95], 0, v[134:135]
	s_add_i32 m0, s49, 0x2000
	s_nop 0
	global_load_lds_dwordx4 v[242:243], off
	v_lshl_add_u64 v[242:243], s[26:27], 0, v[130:131]
	s_mov_b32 m0, s17
	s_nop 0
	global_load_lds_dwordx4 v[242:243], off
	s_mov_b32 m0, s36
	s_nop 0
	global_load_lds_dwordx4 v[244:245], off
	s_waitcnt vmcnt(8)
	s_waitcnt lgkmcnt(0)
	s_barrier
	s_setprio 1
	s_waitcnt lgkmcnt(0)
	v_mfma_f32_16x16x32_bf16 v[62:65], v[140:143], v[188:191], v[62:65]
	v_mfma_f32_16x16x32_bf16 v[58:61], v[154:157], v[188:191], v[58:61]
	v_mfma_f32_16x16x32_bf16 v[50:53], v[140:143], v[196:199], v[50:53]
	v_mfma_f32_16x16x32_bf16 v[42:45], v[154:157], v[196:199], v[42:45]
	v_mfma_f32_16x16x32_bf16 v[34:37], v[140:143], v[226:229], v[34:37]
	v_mfma_f32_16x16x32_bf16 v[26:29], v[154:157], v[226:229], v[26:29]
	v_mfma_f32_16x16x32_bf16 v[18:21], v[140:143], v[234:237], v[18:21]
	v_mfma_f32_16x16x32_bf16 v[10:13], v[154:157], v[234:237], v[10:13]
	v_mfma_f32_16x16x32_bf16 v[62:65], v[144:147], v[192:195], v[62:65]
	v_mfma_f32_16x16x32_bf16 v[58:61], v[158:161], v[192:195], v[58:61]
	v_mfma_f32_16x16x32_bf16 v[50:53], v[144:147], v[222:225], v[50:53]
	v_mfma_f32_16x16x32_bf16 v[42:45], v[158:161], v[222:225], v[42:45]
	v_mfma_f32_16x16x32_bf16 v[34:37], v[144:147], v[230:233], v[34:37]
	v_mfma_f32_16x16x32_bf16 v[26:29], v[158:161], v[230:233], v[26:29]
	v_mfma_f32_16x16x32_bf16 v[18:21], v[144:147], v[238:241], v[18:21]
	v_mfma_f32_16x16x32_bf16 v[10:13], v[158:161], v[238:241], v[10:13]
	s_setprio 0
	s_setprio 1
	v_mfma_f32_16x16x32_bf16 v[54:57], v[162:165], v[188:191], v[54:57]
	v_mfma_f32_16x16x32_bf16 v[46:49], v[180:183], v[188:191], v[46:49]
	v_mfma_f32_16x16x32_bf16 v[38:41], v[162:165], v[196:199], v[38:41]
	v_mfma_f32_16x16x32_bf16 v[30:33], v[180:183], v[196:199], v[30:33]
	v_mfma_f32_16x16x32_bf16 v[22:25], v[162:165], v[226:229], v[22:25]
	v_mfma_f32_16x16x32_bf16 v[14:17], v[180:183], v[226:229], v[14:17]
	v_mfma_f32_16x16x32_bf16 v[6:9], v[162:165], v[234:237], v[6:9]
	v_mfma_f32_16x16x32_bf16 v[2:5], v[180:183], v[234:237], v[2:5]
	v_mfma_f32_16x16x32_bf16 v[54:57], v[176:179], v[192:195], v[54:57]
	v_mfma_f32_16x16x32_bf16 v[46:49], v[184:187], v[192:195], v[46:49]
	v_mfma_f32_16x16x32_bf16 v[38:41], v[176:179], v[222:225], v[38:41]
	v_mfma_f32_16x16x32_bf16 v[30:33], v[184:187], v[222:225], v[30:33]
	v_mfma_f32_16x16x32_bf16 v[22:25], v[176:179], v[230:233], v[22:25]
	v_mfma_f32_16x16x32_bf16 v[14:17], v[184:187], v[230:233], v[14:17]
	v_mfma_f32_16x16x32_bf16 v[6:9], v[176:179], v[238:241], v[6:9]
	v_mfma_f32_16x16x32_bf16 v[2:5], v[184:187], v[238:241], v[2:5]
	s_setprio 0
	s_barrier
; #define PG8_STAGE(bufoff, gbase, voff) do { _Pragma("unroll") for (int _i = 0; _i < 2; ++_i) \
;         __builtin_amdgcn_global_load_lds((const unsigned*)((const char*)(gbase) + (voff)[_i]), (LAS unsigned*)(lds + (bufoff) + ldsw + _i * 8192), 16, 0, 0); } while (0)
; #define PG8_LDA(dst, b, h) do { _Pragma("unroll") for (int m = 0; m < 4; ++m) _Pragma("unroll") for (int k = 0; k < 2; ++k) dst[m][k] = *(const LAS bf16x8*)(lds + PG8_SA(b, h) + aoff + m * 2048 + k * 1024); } while (0)
; #define PG8_LDB(dst, b, h) do { _Pragma("unroll") for (int n = 0; n < 2; ++n) _Pragma("unroll") for (int k = 0; k < 2; ++k) dst[n][k] = *(const LAS bf16x8*)(lds + PG8_SB(b, h) + boff + n * 2048 + k * 1024); } while (0)
; #define PG8_MMA(ai, bj, At, Bt) do { __builtin_amdgcn_s_setprio(1); _Pragma("unroll") for (int m = 0; m < 4; ++m) _Pragma("unroll") for (int n = 0; n < 2; ++n) _Pragma("unroll") for (int k = 0; k < 2; ++k) \
;         acc[ai][bj][m][n] = __builtin_amdgcn_mfma_f32_16x16x32_bf16(Bt[n][k], At[m][k], acc[ai][bj][m][n], 0, 0, 0); __builtin_amdgcn_s_setprio(0); } while (0)
; #define PG8_WAIT_V(n) asm volatile("s_waitcnt vmcnt(" #n ")" ::: "memory")
; #define PG8_WAIT_L(n) asm volatile("s_waitcnt lgkmcnt(" #n ")" ::: "memory")
; #define PG8_BAR __builtin_amdgcn_s_barrier()
; #define PG8_SCHED __builtin_amdgcn_sched_barrier(0)
; template <class Epi>
; __device__ __forceinline__ void gemm_phase(LAS unsigned char* lds, const Sched& S, const Epi& E) {
;     ...
;             PG8_LDB(B0, 1, 0); PG8_LDB(B1, 1, 1); PG8_SCHED; PG8_LDA(At, 1, 0); PG8_STAGE(PG8_SA(0, 1), a2 + hstepA, voffA);
;             PG8_WAIT_V(8); PG8_WAIT_L(0); PG8_BAR; PG8_MMA(0, 0, At, B0); PG8_MMA(0, 1, At, B1); PG8_BAR; PG8_SCHED;
;             PG8_LDA(At, 1, 1); PG8_STAGE(PG8_SB(1, 0), b3, voffB); PG8_STAGE(PG8_SB(1, 1), b3 + hstepB, voffB); PG8_STAGE(PG8_SA(1, 0), a3, voffA);
;             PG8_WAIT_V(8); PG8_WAIT_L(0); PG8_BAR; PG8_MMA(1, 0, At, B0); PG8_MMA(1, 1, At, B1); PG8_BAR; PG8_SCHED;
	s_add_i32 s49, 0, 0x18000
	v_add_u32_e32 v153, s49, v149
	s_add_i32 s69, 0, 0x1c000
	ds_read_b128 v[140:143], v153
	ds_read_b128 v[144:147], v153 offset:1024
	ds_read_b128 v[154:157], v153 offset:2048
	ds_read_b128 v[158:161], v153 offset:3072
	v_add_u32_e32 v153, s69, v149
	ds_read_b128 v[162:165], v153
	ds_read_b128 v[176:179], v153 offset:1024
	ds_read_b128 v[180:183], v153 offset:2048
	ds_read_b128 v[184:187], v153 offset:3072
	s_add_u32 s26, s26, 0x80000
	s_addc_u32 s27, s27, 0
	s_mov_b32 m0, s37
	v_lshl_add_u64 v[246:247], s[26:27], 0, v[130:131]
	ds_read_b128 v[188:191], v152 offset:32768
	ds_read_b128 v[192:195], v152 offset:33792
	ds_read_b128 v[196:199], v152 offset:34816
	ds_read_b128 v[222:225], v152 offset:35840
	ds_read_b128 v[226:229], v152 offset:36864
	ds_read_b128 v[230:233], v152 offset:37888
	ds_read_b128 v[234:237], v152 offset:38912
	ds_read_b128 v[238:241], v152 offset:39936
	global_load_lds_dwordx4 v[246:247], off
	v_lshl_add_u64 v[246:247], s[26:27], 0, v[132:133]
	s_mov_b32 m0, s38
	s_nop 0
	global_load_lds_dwordx4 v[246:247], off
	s_waitcnt vmcnt(8)
	s_waitcnt lgkmcnt(0)
	s_barrier
	s_setprio 1
	s_waitcnt lgkmcnt(0)
	v_mfma_f32_16x16x32_bf16 v[126:129], v[140:143], v[188:191], v[126:129]
	v_mfma_f32_16x16x32_bf16 v[122:125], v[154:157], v[188:191], v[122:125]
	v_mfma_f32_16x16x32_bf16 v[114:117], v[140:143], v[196:199], v[114:117]
	v_mfma_f32_16x16x32_bf16 v[106:109], v[154:157], v[196:199], v[106:109]
	v_mfma_f32_16x16x32_bf16 v[98:101], v[140:143], v[226:229], v[98:101]
	v_mfma_f32_16x16x32_bf16 v[90:93], v[154:157], v[226:229], v[90:93]
	v_mfma_f32_16x16x32_bf16 v[82:85], v[140:143], v[234:237], v[82:85]
	v_mfma_f32_16x16x32_bf16 v[74:77], v[154:157], v[234:237], v[74:77]
	v_mfma_f32_16x16x32_bf16 v[126:129], v[144:147], v[192:195], v[126:129]
	v_mfma_f32_16x16x32_bf16 v[122:125], v[158:161], v[192:195], v[122:125]
	v_mfma_f32_16x16x32_bf16 v[114:117], v[144:147], v[222:225], v[114:117]
	v_mfma_f32_16x16x32_bf16 v[106:109], v[158:161], v[222:225], v[106:109]
	v_mfma_f32_16x16x32_bf16 v[98:101], v[144:147], v[230:233], v[98:101]
	v_mfma_f32_16x16x32_bf16 v[90:93], v[158:161], v[230:233], v[90:93]
	v_mfma_f32_16x16x32_bf16 v[82:85], v[144:147], v[238:241], v[82:85]
	v_mfma_f32_16x16x32_bf16 v[74:77], v[158:161], v[238:241], v[74:77]
	s_setprio 0
	s_setprio 1
	v_mfma_f32_16x16x32_bf16 v[118:121], v[162:165], v[188:191], v[118:121]
	v_mfma_f32_16x16x32_bf16 v[110:113], v[180:183], v[188:191], v[110:113]
	v_mfma_f32_16x16x32_bf16 v[102:105], v[162:165], v[196:199], v[102:105]
	v_mfma_f32_16x16x32_bf16 v[94:97], v[180:183], v[196:199], v[94:97]
	v_mfma_f32_16x16x32_bf16 v[86:89], v[162:165], v[226:229], v[86:89]
	v_mfma_f32_16x16x32_bf16 v[78:81], v[180:183], v[226:229], v[78:81]
	v_mfma_f32_16x16x32_bf16 v[70:73], v[162:165], v[234:237], v[70:73]
	v_mfma_f32_16x16x32_bf16 v[66:69], v[180:183], v[234:237], v[66:69]
	v_mfma_f32_16x16x32_bf16 v[118:121], v[176:179], v[192:195], v[118:121]
	v_mfma_f32_16x16x32_bf16 v[110:113], v[184:187], v[192:195], v[110:113]
	v_mfma_f32_16x16x32_bf16 v[102:105], v[176:179], v[222:225], v[102:105]
	v_mfma_f32_16x16x32_bf16 v[94:97], v[184:187], v[222:225], v[94:97]
	v_mfma_f32_16x16x32_bf16 v[86:89], v[176:179], v[230:233], v[86:89]
	v_mfma_f32_16x16x32_bf16 v[78:81], v[184:187], v[230:233], v[78:81]
	v_mfma_f32_16x16x32_bf16 v[70:73], v[176:179], v[238:241], v[70:73]
	v_mfma_f32_16x16x32_bf16 v[66:69], v[184:187], v[238:241], v[66:69]
	s_setprio 0
	s_barrier
	s_add_i32 s26, s49, s35
	v_lshl_add_u64 v[166:167], v[166:167], 0, s[0:1]
	s_mov_b32 m0, s26
	ds_read_b128 v[188:191], v152 offset:49152
	ds_read_b128 v[192:195], v152 offset:50176
	ds_read_b128 v[196:199], v152 offset:51200
	ds_read_b128 v[222:225], v152 offset:52224
	ds_read_b128 v[226:229], v152 offset:53248
	ds_read_b128 v[230:233], v152 offset:54272
	ds_read_b128 v[234:237], v152 offset:55296
	ds_read_b128 v[238:241], v152 offset:56320
	global_load_lds_dwordx4 v[166:167], off
	s_add_i32 m0, s26, 0x2000
	s_add_u32 s24, s24, 0x80080
	v_lshl_add_u64 v[166:167], v[200:201], 0, s[0:1]
	s_addc_u32 s25, s25, 0
	s_add_i32 s26, s69, s35
	global_load_lds_dwordx4 v[166:167], off
	v_lshl_add_u64 v[166:167], s[24:25], 0, v[168:169]
	s_mov_b32 m0, s26
	s_nop 0
	global_load_lds_dwordx4 v[166:167], off
	v_lshl_add_u64 v[166:167], s[24:25], 0, v[134:135]
	s_add_i32 m0, s26, 0x2000
	s_nop 0
	global_load_lds_dwordx4 v[166:167], off
	v_lshl_add_u64 v[166:167], v[242:243], 0, s[0:1]
	s_mov_b32 m0, s39
	s_nop 0
	global_load_lds_dwordx4 v[166:167], off
	v_lshl_add_u64 v[166:167], v[244:245], 0, s[0:1]
	s_mov_b32 m0, s59
	s_nop 0
	global_load_lds_dwordx4 v[166:167], off
	s_waitcnt vmcnt(8)
	s_waitcnt lgkmcnt(0)
	s_barrier
; #define PG8_STAGE(bufoff, gbase, voff) do { _Pragma("unroll") for (int _i = 0; _i < 2; ++_i) \
;         __builtin_amdgcn_global_load_lds((const unsigned*)((const char*)(gbase) + (voff)[_i]), (LAS unsigned*)(lds + (bufoff) + ldsw + _i * 8192), 16, 0, 0); } while (0)
; #define PG8_LDA(dst, b, h) do { _Pragma("unroll") for (int m = 0; m < 4; ++m) _Pragma("unroll") for (int k = 0; k < 2; ++k) dst[m][k] = *(const LAS bf16x8*)(lds + PG8_SA(b, h) + aoff + m * 2048 + k * 1024); } while (0)
; #define PG8_LDB(dst, b, h) do { _Pragma("unroll") for (int n = 0; n < 2; ++n) _Pragma("unroll") for (int k = 0; k < 2; ++k) dst[n][k] = *(const LAS bf16x8*)(lds + PG8_SB(b, h) + boff + n * 2048 + k * 1024); } while (0)
; #define PG8_WAIT_V(n) asm volatile("s_waitcnt vmcnt(" #n ")" ::: "memory")
; #define PG8_WAIT_L(n) asm volatile("s_waitcnt lgkmcnt(" #n ")" ::: "memory")
; template <class Epi>
; __device__ __forceinline__ void gemm_phase(LAS unsigned char* lds, const Sched& S, const Epi& E) {
;     ...
;         for (int t = 0; t < nt; t += 2) {
;             const bool last = (t == nt - 2);
;             const char* a1 = cA + (size_t)(t + 1) * kstep;
;             const char* a2 = last ? nA : cA + (size_t)(t + 2) * kstep; const char* b2 = last ? nB : cB + (size_t)(t + 2) * kstep;
;             const char* a3 = a2 + kstep; const char* b3 = b2 + kstep;
;             PG8_LDB(B0, 0, 0); PG8_LDB(B1, 0, 1); PG8_SCHED; PG8_LDA(At, 0, 0); PG8_STAGE(PG8_SA(1, 1), a1 + hstepA, voffA);
;             PG8_WAIT_V(8); PG8_WAIT_L(0); PG8_BAR; PG8_MMA(0, 0, At, B0); PG8_MMA(0, 1, At, B1); PG8_BAR; PG8_SCHED;
;             PG8_LDA(At, 0, 1); PG8_STAGE(PG8_SB(0, 0), b2, voffB); PG8_STAGE(PG8_SB(0, 1), b2 + hstepB, voffB); PG8_STAGE(PG8_SA(0, 0), a2, voffA);
;             PG8_WAIT_V(8); PG8_WAIT_L(0); PG8_BAR; PG8_MMA(1, 0, At, B0); PG8_MMA(1, 1, At, B1); PG8_BAR; PG8_SCHED;
;             PG8_LDB(B0, 1, 0); PG8_LDB(B1, 1, 1); PG8_SCHED; PG8_LDA(At, 1, 0); PG8_STAGE(PG8_SA(0, 1), a2 + hstepA, voffA);
;             PG8_WAIT_V(8); PG8_WAIT_L(0); PG8_BAR; PG8_MMA(0, 0, At, B0); PG8_MMA(0, 1, At, B1); PG8_BAR; PG8_SCHED;
;             PG8_LDA(At, 1, 1); PG8_STAGE(PG8_SB(1, 0), b3, voffB); PG8_STAGE(PG8_SB(1, 1), b3 + hstepB, voffB); PG8_STAGE(PG8_SA(1, 0), a3, voffA);
;             PG8_WAIT_V(8); PG8_WAIT_L(0); PG8_BAR; PG8_MMA(1, 0, At, B0); PG8_MMA(1, 1, At, B1); PG8_BAR; PG8_SCHED;
;         }
	s_setprio 1
	s_waitcnt lgkmcnt(0)
	v_mfma_f32_16x16x32_bf16 v[62:65], v[140:143], v[188:191], v[62:65]
	v_mfma_f32_16x16x32_bf16 v[58:61], v[154:157], v[188:191], v[58:61]
	v_mfma_f32_16x16x32_bf16 v[50:53], v[140:143], v[196:199], v[50:53]
	v_mfma_f32_16x16x32_bf16 v[42:45], v[154:157], v[196:199], v[42:45]
	v_mfma_f32_16x16x32_bf16 v[34:37], v[140:143], v[226:229], v[34:37]
	v_mfma_f32_16x16x32_bf16 v[26:29], v[154:157], v[226:229], v[26:29]
	v_mfma_f32_16x16x32_bf16 v[18:21], v[140:143], v[234:237], v[18:21]
	v_mfma_f32_16x16x32_bf16 v[10:13], v[154:157], v[234:237], v[10:13]
	v_mfma_f32_16x16x32_bf16 v[62:65], v[144:147], v[192:195], v[62:65]
	v_mfma_f32_16x16x32_bf16 v[58:61], v[158:161], v[192:195], v[58:61]
	v_mfma_f32_16x16x32_bf16 v[50:53], v[144:147], v[222:225], v[50:53]
	v_mfma_f32_16x16x32_bf16 v[42:45], v[158:161], v[222:225], v[42:45]
	v_mfma_f32_16x16x32_bf16 v[34:37], v[144:147], v[230:233], v[34:37]
	v_mfma_f32_16x16x32_bf16 v[26:29], v[158:161], v[230:233], v[26:29]
	v_mfma_f32_16x16x32_bf16 v[18:21], v[144:147], v[238:241], v[18:21]
	v_mfma_f32_16x16x32_bf16 v[10:13], v[158:161], v[238:241], v[10:13]
	s_setprio 0
	s_setprio 1
	v_mfma_f32_16x16x32_bf16 v[54:57], v[162:165], v[188:191], v[54:57]
	v_mfma_f32_16x16x32_bf16 v[46:49], v[180:183], v[188:191], v[46:49]
	v_mfma_f32_16x16x32_bf16 v[38:41], v[162:165], v[196:199], v[38:41]
	v_mfma_f32_16x16x32_bf16 v[30:33], v[180:183], v[196:199], v[30:33]
	v_mfma_f32_16x16x32_bf16 v[22:25], v[162:165], v[226:229], v[22:25]
	v_mfma_f32_16x16x32_bf16 v[14:17], v[180:183], v[226:229], v[14:17]
	v_mfma_f32_16x16x32_bf16 v[6:9], v[162:165], v[234:237], v[6:9]
	v_mfma_f32_16x16x32_bf16 v[2:5], v[180:183], v[234:237], v[2:5]
	v_mfma_f32_16x16x32_bf16 v[54:57], v[176:179], v[192:195], v[54:57]
	v_mfma_f32_16x16x32_bf16 v[46:49], v[184:187], v[192:195], v[46:49]
	v_mfma_f32_16x16x32_bf16 v[38:41], v[176:179], v[222:225], v[38:41]
	v_mfma_f32_16x16x32_bf16 v[30:33], v[184:187], v[222:225], v[30:33]
	v_mfma_f32_16x16x32_bf16 v[22:25], v[176:179], v[230:233], v[22:25]
	v_mfma_f32_16x16x32_bf16 v[14:17], v[184:187], v[230:233], v[14:17]
	v_mfma_f32_16x16x32_bf16 v[6:9], v[176:179], v[238:241], v[6:9]
	v_mfma_f32_16x16x32_bf16 v[2:5], v[184:187], v[238:241], v[2:5]
	s_setprio 0
	s_barrier
	s_add_i32 s68, s68, 2
	s_add_u32 s22, s22, 0x100
	s_addc_u32 s23, s23, 0
	s_add_u32 s9, s9, 0x100
	s_addc_u32 s11, s11, 0
	s_cmp_gt_u32 s68, 29
	s_cbranch_scc0 .LBB0_735
	s_branch .Lpeel_exit_qkv
.Ltail_peel_qkv:
	s_add_u32 s24, s22, 0xfff80080
	s_addc_u32 s25, s23, -1
	s_add_i32 s49, 0, 0x10000
	s_cmp_eq_u32 s68, 28
	s_cselect_b32 s27, s19, s25
	s_cselect_b32 s26, s18, s24
	v_add_u32_e32 v153, s49, v149
	s_cselect_b32 s25, s21, s11
	s_cselect_b32 s24, s20, s9
	s_add_i32 s69, 0, 0x14000
	ds_read_b128 v[140:143], v153
	ds_read_b128 v[144:147], v153 offset:1024
	ds_read_b128 v[154:157], v153 offset:2048
	ds_read_b128 v[158:161], v153 offset:3072
	v_add_u32_e32 v153, s69, v149
	ds_read_b128 v[162:165], v153
	ds_read_b128 v[176:179], v153 offset:1024
	ds_read_b128 v[180:183], v153 offset:2048
	ds_read_b128 v[184:187], v153 offset:3072
	v_lshl_add_u64 v[166:167], s[22:23], 0, v[136:137]
	s_add_i32 m0, s17, 0xc000
	ds_read_b128 v[188:191], v152
	ds_read_b128 v[192:195], v152 offset:1024
	ds_read_b128 v[196:199], v152 offset:2048
	ds_read_b128 v[222:225], v152 offset:3072
	ds_read_b128 v[226:229], v152 offset:4096
	ds_read_b128 v[230:233], v152 offset:5120
	ds_read_b128 v[234:237], v152 offset:6144
	ds_read_b128 v[238:241], v152 offset:7168
	global_load_lds_dwordx4 v[166:167], off
	v_lshl_add_u64 v[166:167], s[22:23], 0, v[138:139]
	s_add_i32 m0, s17, 0xe000
	s_nop 0
	global_load_lds_dwordx4 v[166:167], off
	s_waitcnt vmcnt(8)
	s_waitcnt lgkmcnt(0)
	s_barrier
	s_setprio 1
	s_waitcnt lgkmcnt(0)
	s_cmp_eq_u64 s[6:7], 0
	s_cbranch_scc1 .Ltskip_qkvp_0
	v_mfma_f32_16x16x32_bf16 v[126:129], v[140:143], v[188:191], 0
	v_mfma_f32_16x16x32_bf16 v[122:125], v[154:157], v[188:191], 0
	v_mfma_f32_16x16x32_bf16 v[114:117], v[140:143], v[196:199], 0
	v_mfma_f32_16x16x32_bf16 v[106:109], v[154:157], v[196:199], 0
	v_mfma_f32_16x16x32_bf16 v[98:101], v[140:143], v[226:229], 0
	v_mfma_f32_16x16x32_bf16 v[90:93], v[154:157], v[226:229], 0
	v_mfma_f32_16x16x32_bf16 v[82:85], v[140:143], v[234:237], 0
	v_mfma_f32_16x16x32_bf16 v[74:77], v[154:157], v[234:237], 0
	v_mfma_f32_16x16x32_bf16 v[126:129], v[144:147], v[192:195], v[126:129]
	v_mfma_f32_16x16x32_bf16 v[122:125], v[158:161], v[192:195], v[122:125]
	v_mfma_f32_16x16x32_bf16 v[114:117], v[144:147], v[222:225], v[114:117]
	v_mfma_f32_16x16x32_bf16 v[106:109], v[158:161], v[222:225], v[106:109]
	v_mfma_f32_16x16x32_bf16 v[98:101], v[144:147], v[230:233], v[98:101]
	v_mfma_f32_16x16x32_bf16 v[90:93], v[158:161], v[230:233], v[90:93]
	v_mfma_f32_16x16x32_bf16 v[82:85], v[144:147], v[238:241], v[82:85]
	v_mfma_f32_16x16x32_bf16 v[74:77], v[158:161], v[238:241], v[74:77]
	s_setprio 0
	s_setprio 1
	v_mfma_f32_16x16x32_bf16 v[118:121], v[162:165], v[188:191], 0
	v_mfma_f32_16x16x32_bf16 v[110:113], v[180:183], v[188:191], 0
	v_mfma_f32_16x16x32_bf16 v[102:105], v[162:165], v[196:199], 0
	v_mfma_f32_16x16x32_bf16 v[94:97], v[180:183], v[196:199], 0
	v_mfma_f32_16x16x32_bf16 v[86:89], v[162:165], v[226:229], 0
	v_mfma_f32_16x16x32_bf16 v[78:81], v[180:183], v[226:229], 0
	v_mfma_f32_16x16x32_bf16 v[70:73], v[162:165], v[234:237], 0
	v_mfma_f32_16x16x32_bf16 v[66:69], v[180:183], v[234:237], 0
	v_mfma_f32_16x16x32_bf16 v[118:121], v[176:179], v[192:195], v[118:121]
	v_mfma_f32_16x16x32_bf16 v[110:113], v[184:187], v[192:195], v[110:113]
	v_mfma_f32_16x16x32_bf16 v[102:105], v[176:179], v[222:225], v[102:105]
	v_mfma_f32_16x16x32_bf16 v[94:97], v[184:187], v[222:225], v[94:97]
	v_mfma_f32_16x16x32_bf16 v[86:89], v[176:179], v[230:233], v[86:89]
	v_mfma_f32_16x16x32_bf16 v[78:81], v[184:187], v[230:233], v[78:81]
	v_mfma_f32_16x16x32_bf16 v[70:73], v[176:179], v[238:241], v[70:73]
	v_mfma_f32_16x16x32_bf16 v[66:69], v[184:187], v[238:241], v[66:69]
; #define PG8_STAGE(bufoff, gbase, voff) do { _Pragma("unroll") for (int _i = 0; _i < 2; ++_i) \
;         __builtin_amdgcn_global_load_lds((const unsigned*)((const char*)(gbase) + (voff)[_i]), (LAS unsigned*)(lds + (bufoff) + ldsw + _i * 8192), 16, 0, 0); } while (0)
; #define PG8_LDA(dst, b, h) do { _Pragma("unroll") for (int m = 0; m < 4; ++m) _Pragma("unroll") for (int k = 0; k < 2; ++k) dst[m][k] = *(const LAS bf16x8*)(lds + PG8_SA(b, h) + aoff + m * 2048 + k * 1024); } while (0)
; #define PG8_LDB(dst, b, h) do { _Pragma("unroll") for (int n = 0; n < 2; ++n) _Pragma("unroll") for (int k = 0; k < 2; ++k) dst[n][k] = *(const LAS bf16x8*)(lds + PG8_SB(b, h) + boff + n * 2048 + k * 1024); } while (0)
; #define PG8_MMA(ai, bj, At, Bt) do { __builtin_amdgcn_s_setprio(1); _Pragma("unroll") for (int m = 0; m < 4; ++m) _Pragma("unroll") for (int n = 0; n < 2; ++n) _Pragma("unroll") for (int k = 0; k < 2; ++k) \
;         acc[ai][bj][m][n] = __builtin_amdgcn_mfma_f32_16x16x32_bf16(Bt[n][k], At[m][k], acc[ai][bj][m][n], 0, 0, 0); __builtin_amdgcn_s_setprio(0); } while (0)
; #define PG8_WAIT_V(n) asm volatile("s_waitcnt vmcnt(" #n ")" ::: "memory")
; #define PG8_WAIT_L(n) asm volatile("s_waitcnt lgkmcnt(" #n ")" ::: "memory")
; #define PG8_BAR __builtin_amdgcn_s_barrier()
; #define PG8_SCHED __builtin_amdgcn_sched_barrier(0)
; template <class Epi>
; __device__ __forceinline__ void gemm_phase(LAS unsigned char* lds, const Sched& S, const Epi& E) {
;     ...
;             PG8_LDA(At, 0, 1); PG8_STAGE(PG8_SB(0, 0), b2, voffB); PG8_STAGE(PG8_SB(0, 1), b2 + hstepB, voffB); PG8_STAGE(PG8_SA(0, 0), a2, voffA);
;             PG8_WAIT_V(8); PG8_WAIT_L(0); PG8_BAR; PG8_MMA(1, 0, At, B0); PG8_MMA(1, 1, At, B1); PG8_BAR; PG8_SCHED;
;             PG8_LDB(B0, 1, 0); PG8_LDB(B1, 1, 1); PG8_SCHED; PG8_LDA(At, 1, 0); PG8_STAGE(PG8_SA(0, 1), a2 + hstepA, voffA);
;             PG8_WAIT_V(8); PG8_WAIT_L(0); PG8_BAR; PG8_MMA(0, 0, At, B0); PG8_MMA(0, 1, At, B1); PG8_BAR; PG8_SCHED;
.Ltskip_qkvp_0:
	s_setprio 0
	s_barrier
	s_add_i32 s49, s49, s35
	v_lshl_add_u64 v[166:167], s[24:25], 0, v[168:169]
	s_mov_b32 m0, s49
	ds_read_b128 v[188:191], v152 offset:16384
	ds_read_b128 v[192:195], v152 offset:17408
	ds_read_b128 v[196:199], v152 offset:18432
	ds_read_b128 v[222:225], v152 offset:19456
	ds_read_b128 v[226:229], v152 offset:20480
	ds_read_b128 v[230:233], v152 offset:21504
	ds_read_b128 v[234:237], v152 offset:22528
	ds_read_b128 v[238:241], v152 offset:23552
	global_load_lds_dwordx4 v[166:167], off
	s_add_i32 m0, s49, 0x2000
	s_add_u32 s94, s24, 0x80000
	v_lshl_add_u64 v[200:201], s[24:25], 0, v[134:135]
	s_addc_u32 s95, s25, 0
	s_add_i32 s49, s69, s35
	global_load_lds_dwordx4 v[200:201], off
	v_lshl_add_u64 v[242:243], s[94:95], 0, v[168:169]
	s_mov_b32 m0, s49
	v_lshl_add_u64 v[244:245], s[26:27], 0, v[132:133]
	global_load_lds_dwordx4 v[242:243], off
	v_lshl_add_u64 v[242:243], s[94:95], 0, v[134:135]
	s_add_i32 m0, s49, 0x2000
	s_nop 0
	global_load_lds_dwordx4 v[242:243], off
	v_lshl_add_u64 v[242:243], s[26:27], 0, v[130:131]
	s_mov_b32 m0, s17
	s_nop 0
	global_load_lds_dwordx4 v[242:243], off
	s_mov_b32 m0, s36
	s_nop 0
	global_load_lds_dwordx4 v[244:245], off
	s_waitcnt vmcnt(8)
	s_waitcnt lgkmcnt(0)
	s_barrier
	s_setprio 1
	s_waitcnt lgkmcnt(0)
	s_setprio 0
	s_setprio 1
	s_setprio 0
	s_barrier
	s_add_i32 s49, 0, 0x18000
	v_add_u32_e32 v153, s49, v149
	s_add_i32 s69, 0, 0x1c000
	ds_read_b128 v[140:143], v153
	ds_read_b128 v[144:147], v153 offset:1024
	ds_read_b128 v[154:157], v153 offset:2048
	ds_read_b128 v[158:161], v153 offset:3072
	v_add_u32_e32 v153, s69, v149
	ds_read_b128 v[162:165], v153
	ds_read_b128 v[176:179], v153 offset:1024
	ds_read_b128 v[180:183], v153 offset:2048
	ds_read_b128 v[184:187], v153 offset:3072
	s_add_u32 s26, s26, 0x80000
	s_addc_u32 s27, s27, 0
	s_mov_b32 m0, s37
	v_lshl_add_u64 v[246:247], s[26:27], 0, v[130:131]
	ds_read_b128 v[188:191], v152 offset:32768
	ds_read_b128 v[192:195], v152 offset:33792
	ds_read_b128 v[196:199], v152 offset:34816
	ds_read_b128 v[222:225], v152 offset:35840
	ds_read_b128 v[226:229], v152 offset:36864
	ds_read_b128 v[230:233], v152 offset:37888
	ds_read_b128 v[234:237], v152 offset:38912
	ds_read_b128 v[238:241], v152 offset:39936
	global_load_lds_dwordx4 v[246:247], off
	v_lshl_add_u64 v[246:247], s[26:27], 0, v[132:133]
	s_mov_b32 m0, s38
	s_nop 0
	global_load_lds_dwordx4 v[246:247], off
	s_waitcnt vmcnt(8)
	s_waitcnt lgkmcnt(0)
	s_barrier
	s_setprio 1
	s_waitcnt lgkmcnt(0)
	s_cmp_eq_u64 s[6:7], 0
	s_cbranch_scc1 .Ltskip_qkvp_1
	v_mfma_f32_16x16x32_bf16 v[126:129], v[140:143], v[188:191], v[126:129]
	v_mfma_f32_16x16x32_bf16 v[122:125], v[154:157], v[188:191], v[122:125]
	v_mfma_f32_16x16x32_bf16 v[114:117], v[140:143], v[196:199], v[114:117]
	v_mfma_f32_16x16x32_bf16 v[106:109], v[154:157], v[196:199], v[106:109]
	v_mfma_f32_16x16x32_bf16 v[98:101], v[140:143], v[226:229], v[98:101]
	v_mfma_f32_16x16x32_bf16 v[90:93], v[154:157], v[226:229], v[90:93]
	v_mfma_f32_16x16x32_bf16 v[82:85], v[140:143], v[234:237], v[82:85]
	v_mfma_f32_16x16x32_bf16 v[74:77], v[154:157], v[234:237], v[74:77]
	v_mfma_f32_16x16x32_bf16 v[126:129], v[144:147], v[192:195], v[126:129]
	v_mfma_f32_16x16x32_bf16 v[122:125], v[158:161], v[192:195], v[122:125]
	v_mfma_f32_16x16x32_bf16 v[114:117], v[144:147], v[222:225], v[114:117]
	v_mfma_f32_16x16x32_bf16 v[106:109], v[158:161], v[222:225], v[106:109]
	v_mfma_f32_16x16x32_bf16 v[98:101], v[144:147], v[230:233], v[98:101]
	v_mfma_f32_16x16x32_bf16 v[90:93], v[158:161], v[230:233], v[90:93]
	v_mfma_f32_16x16x32_bf16 v[82:85], v[144:147], v[238:241], v[82:85]
	v_mfma_f32_16x16x32_bf16 v[74:77], v[158:161], v[238:241], v[74:77]
	s_setprio 0
	s_setprio 1
	v_mfma_f32_16x16x32_bf16 v[118:121], v[162:165], v[188:191], v[118:121]
	v_mfma_f32_16x16x32_bf16 v[110:113], v[180:183], v[188:191], v[110:113]
	v_mfma_f32_16x16x32_bf16 v[102:105], v[162:165], v[196:199], v[102:105]
	v_mfma_f32_16x16x32_bf16 v[94:97], v[180:183], v[196:199], v[94:97]
	v_mfma_f32_16x16x32_bf16 v[86:89], v[162:165], v[226:229], v[86:89]
	v_mfma_f32_16x16x32_bf16 v[78:81], v[180:183], v[226:229], v[78:81]
	v_mfma_f32_16x16x32_bf16 v[70:73], v[162:165], v[234:237], v[70:73]
	v_mfma_f32_16x16x32_bf16 v[66:69], v[180:183], v[234:237], v[66:69]
	v_mfma_f32_16x16x32_bf16 v[118:121], v[176:179], v[192:195], v[118:121]
	v_mfma_f32_16x16x32_bf16 v[110:113], v[184:187], v[192:195], v[110:113]
	v_mfma_f32_16x16x32_bf16 v[102:105], v[176:179], v[222:225], v[102:105]
	v_mfma_f32_16x16x32_bf16 v[94:97], v[184:187], v[222:225], v[94:97]
	v_mfma_f32_16x16x32_bf16 v[86:89], v[176:179], v[230:233], v[86:89]
	v_mfma_f32_16x16x32_bf16 v[78:81], v[184:187], v[230:233], v[78:81]
	v_mfma_f32_16x16x32_bf16 v[70:73], v[176:179], v[238:241], v[70:73]
	v_mfma_f32_16x16x32_bf16 v[66:69], v[184:187], v[238:241], v[66:69]
; #define PG8_STAGE(bufoff, gbase, voff) do { _Pragma("unroll") for (int _i = 0; _i < 2; ++_i) \
;         __builtin_amdgcn_global_load_lds((const unsigned*)((const char*)(gbase) + (voff)[_i]), (LAS unsigned*)(lds + (bufoff) + ldsw + _i * 8192), 16, 0, 0); } while (0)
; #define PG8_LDA(dst, b, h) do { _Pragma("unroll") for (int m = 0; m < 4; ++m) _Pragma("unroll") for (int k = 0; k < 2; ++k) dst[m][k] = *(const LAS bf16x8*)(lds + PG8_SA(b, h) + aoff + m * 2048 + k * 1024); } while (0)
; #define PG8_LDB(dst, b, h) do { _Pragma("unroll") for (int n = 0; n < 2; ++n) _Pragma("unroll") for (int k = 0; k < 2; ++k) dst[n][k] = *(const LAS bf16x8*)(lds + PG8_SB(b, h) + boff + n * 2048 + k * 1024); } while (0)
; #define PG8_WAIT_V(n) asm volatile("s_waitcnt vmcnt(" #n ")" ::: "memory")
; #define PG8_WAIT_L(n) asm volatile("s_waitcnt lgkmcnt(" #n ")" ::: "memory")
; template <class Epi>
; __device__ __forceinline__ void gemm_phase(LAS unsigned char* lds, const Sched& S, const Epi& E) {
;     ...
;         for (int t = 0; t < nt; t += 2) {
;             const bool last = (t == nt - 2);
;             const char* a1 = cA + (size_t)(t + 1) * kstep;
;             const char* a2 = last ? nA : cA + (size_t)(t + 2) * kstep; const char* b2 = last ? nB : cB + (size_t)(t + 2) * kstep;
;             const char* a3 = a2 + kstep; const char* b3 = b2 + kstep;
;             PG8_LDB(B0, 0, 0); PG8_LDB(B1, 0, 1); PG8_SCHED; PG8_LDA(At, 0, 0); PG8_STAGE(PG8_SA(1, 1), a1 + hstepA, voffA);
;             PG8_WAIT_V(8); PG8_WAIT_L(0); PG8_BAR; PG8_MMA(0, 0, At, B0); PG8_MMA(0, 1, At, B1); PG8_BAR; PG8_SCHED;
;             PG8_LDA(At, 0, 1); PG8_STAGE(PG8_SB(0, 0), b2, voffB); PG8_STAGE(PG8_SB(0, 1), b2 + hstepB, voffB); PG8_STAGE(PG8_SA(0, 0), a2, voffA);
;             PG8_WAIT_V(8); PG8_WAIT_L(0); PG8_BAR; PG8_MMA(1, 0, At, B0); PG8_MMA(1, 1, At, B1); PG8_BAR; PG8_SCHED;
;             PG8_LDB(B0, 1, 0); PG8_LDB(B1, 1, 1); PG8_SCHED; PG8_LDA(At, 1, 0); PG8_STAGE(PG8_SA(0, 1), a2 + hstepA, voffA);
;             PG8_WAIT_V(8); PG8_WAIT_L(0); PG8_BAR; PG8_MMA(0, 0, At, B0); PG8_MMA(0, 1, At, B1); PG8_BAR; PG8_SCHED;
;             PG8_LDA(At, 1, 1); PG8_STAGE(PG8_SB(1, 0), b3, voffB); PG8_STAGE(PG8_SB(1, 1), b3 + hstepB, voffB); PG8_STAGE(PG8_SA(1, 0), a3, voffA);
;             PG8_WAIT_V(8); PG8_WAIT_L(0); PG8_BAR; PG8_MMA(1, 0, At, B0); PG8_MMA(1, 1, At, B1); PG8_BAR; PG8_SCHED;
;         }
.Ltskip_qkvp_1:
	s_setprio 0
	s_barrier
	s_add_i32 s26, s49, s35
	v_lshl_add_u64 v[166:167], v[166:167], 0, s[0:1]
	s_mov_b32 m0, s26
	ds_read_b128 v[188:191], v152 offset:49152
	ds_read_b128 v[192:195], v152 offset:50176
	ds_read_b128 v[196:199], v152 offset:51200
	ds_read_b128 v[222:225], v152 offset:52224
	ds_read_b128 v[226:229], v152 offset:53248
	ds_read_b128 v[230:233], v152 offset:54272
	ds_read_b128 v[234:237], v152 offset:55296
	ds_read_b128 v[238:241], v152 offset:56320
	global_load_lds_dwordx4 v[166:167], off
	s_add_i32 m0, s26, 0x2000
	s_add_u32 s24, s24, 0x80080
	v_lshl_add_u64 v[166:167], v[200:201], 0, s[0:1]
	s_addc_u32 s25, s25, 0
	s_add_i32 s26, s69, s35
	global_load_lds_dwordx4 v[166:167], off
	v_lshl_add_u64 v[166:167], s[24:25], 0, v[168:169]
	s_mov_b32 m0, s26
	s_nop 0
	global_load_lds_dwordx4 v[166:167], off
	v_lshl_add_u64 v[166:167], s[24:25], 0, v[134:135]
	s_add_i32 m0, s26, 0x2000
	s_nop 0
	global_load_lds_dwordx4 v[166:167], off
	v_lshl_add_u64 v[166:167], v[242:243], 0, s[0:1]
	s_mov_b32 m0, s39
	s_nop 0
	global_load_lds_dwordx4 v[166:167], off
	v_lshl_add_u64 v[166:167], v[244:245], 0, s[0:1]
	s_mov_b32 m0, s59
	s_nop 0
	global_load_lds_dwordx4 v[166:167], off
	s_waitcnt vmcnt(8)
	s_waitcnt lgkmcnt(0)
	s_barrier
	s_setprio 1
	s_waitcnt lgkmcnt(0)
	s_setprio 0
	s_setprio 1
	s_setprio 0
	s_barrier
	s_add_i32 s68, s68, 2
	s_add_u32 s22, s22, 0x100
	s_addc_u32 s23, s23, 0
	s_add_u32 s9, s9, 0x100
	s_addc_u32 s11, s11, 0
	s_cmp_gt_u32 s68, 29
	s_cbranch_scc1 .Lpeel_exit_qkv
.Ltail_loop_qkv:
	s_add_u32 s24, s22, 0xfff80080
	s_addc_u32 s25, s23, -1
	s_add_i32 s49, 0, 0x10000
	s_cmp_eq_u32 s68, 28
	s_cselect_b32 s27, s19, s25
	s_cselect_b32 s26, s18, s24
	v_add_u32_e32 v153, s49, v149
	s_cselect_b32 s25, s21, s11
	s_cselect_b32 s24, s20, s9
	s_add_i32 s69, 0, 0x14000
	ds_read_b128 v[140:143], v153
	ds_read_b128 v[144:147], v153 offset:1024
	ds_read_b128 v[154:157], v153 offset:2048
	ds_read_b128 v[158:161], v153 offset:3072
	v_add_u32_e32 v153, s69, v149
	ds_read_b128 v[162:165], v153
	ds_read_b128 v[176:179], v153 offset:1024
	ds_read_b128 v[180:183], v153 offset:2048
	ds_read_b128 v[184:187], v153 offset:3072
	v_lshl_add_u64 v[166:167], s[22:23], 0, v[136:137]
	s_add_i32 m0, s17, 0xc000
	ds_read_b128 v[188:191], v152
	ds_read_b128 v[192:195], v152 offset:1024
	ds_read_b128 v[196:199], v152 offset:2048
	ds_read_b128 v[222:225], v152 offset:3072
	ds_read_b128 v[226:229], v152 offset:4096
	ds_read_b128 v[230:233], v152 offset:5120
	ds_read_b128 v[234:237], v152 offset:6144
	ds_read_b128 v[238:241], v152 offset:7168
	global_load_lds_dwordx4 v[166:167], off
	v_lshl_add_u64 v[166:167], s[22:23], 0, v[138:139]
	s_add_i32 m0, s17, 0xe000
	s_nop 0
	global_load_lds_dwordx4 v[166:167], off
	s_waitcnt vmcnt(8)
	s_waitcnt lgkmcnt(0)
	s_barrier
	s_setprio 1
	s_waitcnt lgkmcnt(0)
	s_cmp_eq_u64 s[6:7], 0
	s_cbranch_scc1 .Ltskip_qkvl_0
	v_mfma_f32_16x16x32_bf16 v[126:129], v[140:143], v[188:191], v[126:129]
	v_mfma_f32_16x16x32_bf16 v[122:125], v[154:157], v[188:191], v[122:125]
	v_mfma_f32_16x16x32_bf16 v[114:117], v[140:143], v[196:199], v[114:117]
	v_mfma_f32_16x16x32_bf16 v[106:109], v[154:157], v[196:199], v[106:109]
	v_mfma_f32_16x16x32_bf16 v[98:101], v[140:143], v[226:229], v[98:101]
	v_mfma_f32_16x16x32_bf16 v[90:93], v[154:157], v[226:229], v[90:93]
	v_mfma_f32_16x16x32_bf16 v[82:85], v[140:143], v[234:237], v[82:85]
	v_mfma_f32_16x16x32_bf16 v[74:77], v[154:157], v[234:237], v[74:77]
	v_mfma_f32_16x16x32_bf16 v[126:129], v[144:147], v[192:195], v[126:129]
	v_mfma_f32_16x16x32_bf16 v[122:125], v[158:161], v[192:195], v[122:125]
	v_mfma_f32_16x16x32_bf16 v[114:117], v[144:147], v[222:225], v[114:117]
	v_mfma_f32_16x16x32_bf16 v[106:109], v[158:161], v[222:225], v[106:109]
	v_mfma_f32_16x16x32_bf16 v[98:101], v[144:147], v[230:233], v[98:101]
	v_mfma_f32_16x16x32_bf16 v[90:93], v[158:161], v[230:233], v[90:93]
	v_mfma_f32_16x16x32_bf16 v[82:85], v[144:147], v[238:241], v[82:85]
	v_mfma_f32_16x16x32_bf16 v[74:77], v[158:161], v[238:241], v[74:77]
	s_setprio 0
	s_setprio 1
	v_mfma_f32_16x16x32_bf16 v[118:121], v[162:165], v[188:191], v[118:121]
	v_mfma_f32_16x16x32_bf16 v[110:113], v[180:183], v[188:191], v[110:113]
	v_mfma_f32_16x16x32_bf16 v[102:105], v[162:165], v[196:199], v[102:105]
	v_mfma_f32_16x16x32_bf16 v[94:97], v[180:183], v[196:199], v[94:97]
	v_mfma_f32_16x16x32_bf16 v[86:89], v[162:165], v[226:229], v[86:89]
	v_mfma_f32_16x16x32_bf16 v[78:81], v[180:183], v[226:229], v[78:81]
	v_mfma_f32_16x16x32_bf16 v[70:73], v[162:165], v[234:237], v[70:73]
	v_mfma_f32_16x16x32_bf16 v[66:69], v[180:183], v[234:237], v[66:69]
	v_mfma_f32_16x16x32_bf16 v[118:121], v[176:179], v[192:195], v[118:121]
	v_mfma_f32_16x16x32_bf16 v[110:113], v[184:187], v[192:195], v[110:113]
	v_mfma_f32_16x16x32_bf16 v[102:105], v[176:179], v[222:225], v[102:105]
	v_mfma_f32_16x16x32_bf16 v[94:97], v[184:187], v[222:225], v[94:97]
	v_mfma_f32_16x16x32_bf16 v[86:89], v[176:179], v[230:233], v[86:89]
	v_mfma_f32_16x16x32_bf16 v[78:81], v[184:187], v[230:233], v[78:81]
	v_mfma_f32_16x16x32_bf16 v[70:73], v[176:179], v[238:241], v[70:73]
	v_mfma_f32_16x16x32_bf16 v[66:69], v[184:187], v[238:241], v[66:69]

; #define PG8_STAGE(bufoff, gbase, voff) do { _Pragma("unroll") for (int _i = 0; _i < 2; ++_i) \
;         __builtin_amdgcn_global_load_lds((const unsigned*)((const char*)(gbase) + (voff)[_i]), (LAS unsigned*)(lds + (bufoff) + ldsw + _i * 8192), 16, 0, 0); } while (0)
; #define PG8_LDA(dst, b, h) do { _Pragma("unroll") for (int m = 0; m < 4; ++m) _Pragma("unroll") for (int k = 0; k < 2; ++k) dst[m][k] = *(const LAS bf16x8*)(lds + PG8_SA(b, h) + aoff + m * 2048 + k * 1024); } while (0)
; #define PG8_MMA(ai, bj, At, Bt) do { __builtin_amdgcn_s_setprio(1); _Pragma("unroll") for (int m = 0; m < 4; ++m) _Pragma("unroll") for (int n = 0; n < 2; ++n) _Pragma("unroll") for (int k = 0; k < 2; ++k) \
;         acc[ai][bj][m][n] = __builtin_amdgcn_mfma_f32_16x16x32_bf16(Bt[n][k], At[m][k], acc[ai][bj][m][n], 0, 0, 0); __builtin_amdgcn_s_setprio(0); } while (0)
; #define PG8_WAIT_V(n) asm volatile("s_waitcnt vmcnt(" #n ")" ::: "memory")
; #define PG8_WAIT_L(n) asm volatile("s_waitcnt lgkmcnt(" #n ")" ::: "memory")
; #define PG8_BAR __builtin_amdgcn_s_barrier()
; #define PG8_SCHED __builtin_amdgcn_sched_barrier(0)
; template <class Epi>
; __device__ __forceinline__ void gemm_phase(LAS unsigned char* lds, const Sched& S, const Epi& E) {
;     ...
;             PG8_LDA(At, 1, 1); PG8_STAGE(PG8_SB(1, 0), b3, voffB); PG8_STAGE(PG8_SB(1, 1), b3 + hstepB, voffB); PG8_STAGE(PG8_SA(1, 0), a3, voffA);
;             PG8_WAIT_V(8); PG8_WAIT_L(0); PG8_BAR; PG8_MMA(1, 0, At, B0); PG8_MMA(1, 1, At, B1); PG8_BAR; PG8_SCHED;
;         }
.Ltskip_qkvl_1:
	s_setprio 0
	s_barrier
	s_add_i32 s26, s49, s35
	v_lshl_add_u64 v[166:167], v[166:167], 0, s[0:1]
	s_mov_b32 m0, s26
	ds_read_b128 v[188:191], v152 offset:49152
	ds_read_b128 v[192:195], v152 offset:50176
	ds_read_b128 v[196:199], v152 offset:51200
	ds_read_b128 v[222:225], v152 offset:52224
	ds_read_b128 v[226:229], v152 offset:53248
	ds_read_b128 v[230:233], v152 offset:54272
	ds_read_b128 v[234:237], v152 offset:55296
	ds_read_b128 v[238:241], v152 offset:56320
	global_load_lds_dwordx4 v[166:167], off
	s_add_i32 m0, s26, 0x2000
	s_add_u32 s24, s24, 0x80080
	v_lshl_add_u64 v[166:167], v[200:201], 0, s[0:1]
	s_addc_u32 s25, s25, 0
	s_add_i32 s26, s69, s35
	global_load_lds_dwordx4 v[166:167], off
	v_lshl_add_u64 v[166:167], s[24:25], 0, v[168:169]
	s_mov_b32 m0, s26
	s_nop 0
	global_load_lds_dwordx4 v[166:167], off
	v_lshl_add_u64 v[166:167], s[24:25], 0, v[134:135]
	s_add_i32 m0, s26, 0x2000
	s_nop 0
	global_load_lds_dwordx4 v[166:167], off
	v_lshl_add_u64 v[166:167], v[242:243], 0, s[0:1]
	s_mov_b32 m0, s39
	s_nop 0
	global_load_lds_dwordx4 v[166:167], off
	v_lshl_add_u64 v[166:167], v[244:245], 0, s[0:1]
	s_mov_b32 m0, s59
	s_nop 0
	global_load_lds_dwordx4 v[166:167], off
	s_waitcnt vmcnt(8)
	s_waitcnt lgkmcnt(0)
	s_barrier
	s_setprio 1
	s_waitcnt lgkmcnt(0)
	s_setprio 0
	s_setprio 1
	s_setprio 0
	s_barrier
	s_add_i32 s68, s68, 2
	s_add_u32 s22, s22, 0x100
	s_addc_u32 s23, s23, 0
	s_add_u32 s9, s9, 0x100
	s_addc_u32 s11, s11, 0
	s_cmp_gt_u32 s68, 29
	s_cbranch_scc0 .Ltail_loop_qkv

; #define PG8_STAGE(bufoff, gbase, voff) do { _Pragma("unroll") for (int _i = 0; _i < 2; ++_i) \
;         __builtin_amdgcn_global_load_lds((const unsigned*)((const char*)(gbase) + (voff)[_i]), (LAS unsigned*)(lds + (bufoff) + ldsw + _i * 8192), 16, 0, 0); } while (0)
; #define PG8_LDA(dst, b, h) do { _Pragma("unroll") for (int m = 0; m < 4; ++m) _Pragma("unroll") for (int k = 0; k < 2; ++k) dst[m][k] = *(const LAS bf16x8*)(lds + PG8_SA(b, h) + aoff + m * 2048 + k * 1024); } while (0)
; #define PG8_LDB(dst, b, h) do { _Pragma("unroll") for (int n = 0; n < 2; ++n) _Pragma("unroll") for (int k = 0; k < 2; ++k) dst[n][k] = *(const LAS bf16x8*)(lds + PG8_SB(b, h) + boff + n * 2048 + k * 1024); } while (0)
; #define PG8_MMA(ai, bj, At, Bt) do { __builtin_amdgcn_s_setprio(1); _Pragma("unroll") for (int m = 0; m < 4; ++m) _Pragma("unroll") for (int n = 0; n < 2; ++n) _Pragma("unroll") for (int k = 0; k < 2; ++k) \
;         acc[ai][bj][m][n] = __builtin_amdgcn_mfma_f32_16x16x32_bf16(Bt[n][k], At[m][k], acc[ai][bj][m][n], 0, 0, 0); __builtin_amdgcn_s_setprio(0); } while (0)
; #define PG8_WAIT_V(n) asm volatile("s_waitcnt vmcnt(" #n ")" ::: "memory")
; #define PG8_WAIT_L(n) asm volatile("s_waitcnt lgkmcnt(" #n ")" ::: "memory")
; #define PG8_BAR __builtin_amdgcn_s_barrier()
; #define PG8_SCHED __builtin_amdgcn_sched_barrier(0)
; template <class Epi>
; __device__ __forceinline__ void gemm_phase(LAS unsigned char* lds, const Sched& S, const Epi& E) {
;     ...
;     for (;;) {
;         const bool has_next = S.next(ui + 1, nxt);
;         const char* nA = has_next ? nxt.A : cA; const char* nB = has_next ? nxt.B : cB;
;         const int nt = cur.nt;
;         for (int t = 0; t < nt; t += 2) {
;             const bool last = (t == nt - 2);
;             const char* a1 = cA + (size_t)(t + 1) * kstep;
;             const char* a2 = last ? nA : cA + (size_t)(t + 2) * kstep; const char* b2 = last ? nB : cB + (size_t)(t + 2) * kstep;
;             const char* a3 = a2 + kstep; const char* b3 = b2 + kstep;
;             PG8_LDB(B0, 0, 0); PG8_LDB(B1, 0, 1); PG8_SCHED; PG8_LDA(At, 0, 0); PG8_STAGE(PG8_SA(1, 1), a1 + hstepA, voffA);
;             PG8_WAIT_V(8); PG8_WAIT_L(0); PG8_BAR; PG8_MMA(0, 0, At, B0); PG8_MMA(0, 1, At, B1); PG8_BAR; PG8_SCHED;
.LBB0_2277:
	s_add_u32 s24, s24, 0x80080
	s_addc_u32 s25, s25, 0
	s_add_u32 s9, s26, 0x100
	v_mov_b32_e32 v2, 0
	s_addc_u32 s11, s27, 0
	s_mov_b32 s69, -2
	s_cmp_eq_u32 s16, 32
	s_cbranch_scc1 .Ltail_peel_gateup
	s_add_u32 s26, s24, 0xfff80080
	s_addc_u32 s27, s25, -1
	s_add_i32 s49, 0, 0x10000
	s_cmp_eq_u32 s69, 28
	s_cselect_b32 s29, s19, s27
	s_cselect_b32 s28, s18, s26
	v_add_u32_e32 v157, s49, v153
	s_cselect_b32 s27, s23, s11
	s_cselect_b32 s26, s22, s9
	s_add_i32 s82, 0, 0x14000
	ds_read_b128 v[140:143], v157
	ds_read_b128 v[144:147], v157 offset:1024
	ds_read_b128 v[148:151], v157 offset:2048
	ds_read_b128 v[158:161], v157 offset:3072
	v_add_u32_e32 v157, s82, v153
	ds_read_b128 v[162:165], v157
	ds_read_b128 v[176:179], v157 offset:1024
	ds_read_b128 v[180:183], v157 offset:2048
	ds_read_b128 v[184:187], v157 offset:3072
	v_lshl_add_u64 v[166:167], s[24:25], 0, v[136:137]
	s_add_i32 m0, s38, 0xc000
	ds_read_b128 v[188:191], v156
	ds_read_b128 v[192:195], v156 offset:1024
	ds_read_b128 v[196:199], v156 offset:2048
	ds_read_b128 v[222:225], v156 offset:3072
	ds_read_b128 v[226:229], v156 offset:4096
	ds_read_b128 v[230:233], v156 offset:5120
	ds_read_b128 v[234:237], v156 offset:6144
	ds_read_b128 v[238:241], v156 offset:7168
	global_load_lds_dwordx4 v[166:167], off
	v_lshl_add_u64 v[166:167], s[24:25], 0, v[138:139]
	s_add_i32 m0, s38, 0xe000
	s_nop 0
	global_load_lds_dwordx4 v[166:167], off
	s_waitcnt vmcnt(8)
	s_waitcnt lgkmcnt(0)
	s_barrier
	s_setprio 1
	s_waitcnt lgkmcnt(0)
	v_mfma_f32_16x16x32_bf16 v[126:129], v[140:143], v[188:191], 0
	v_mfma_f32_16x16x32_bf16 v[118:121], v[148:151], v[188:191], 0
	v_mfma_f32_16x16x32_bf16 v[110:113], v[140:143], v[196:199], 0
	v_mfma_f32_16x16x32_bf16 v[102:105], v[148:151], v[196:199], 0
	v_mfma_f32_16x16x32_bf16 v[94:97], v[140:143], v[226:229], 0
	v_mfma_f32_16x16x32_bf16 v[86:89], v[148:151], v[226:229], 0
	v_mfma_f32_16x16x32_bf16 v[78:81], v[140:143], v[234:237], 0
	v_mfma_f32_16x16x32_bf16 v[70:73], v[148:151], v[234:237], 0
	v_mfma_f32_16x16x32_bf16 v[126:129], v[144:147], v[192:195], v[126:129]
	v_mfma_f32_16x16x32_bf16 v[118:121], v[158:161], v[192:195], v[118:121]
	v_mfma_f32_16x16x32_bf16 v[110:113], v[144:147], v[222:225], v[110:113]
	v_mfma_f32_16x16x32_bf16 v[102:105], v[158:161], v[222:225], v[102:105]
	v_mfma_f32_16x16x32_bf16 v[94:97], v[144:147], v[230:233], v[94:97]
	v_mfma_f32_16x16x32_bf16 v[86:89], v[158:161], v[230:233], v[86:89]
	v_mfma_f32_16x16x32_bf16 v[78:81], v[144:147], v[238:241], v[78:81]
	v_mfma_f32_16x16x32_bf16 v[70:73], v[158:161], v[238:241], v[70:73]
	s_setprio 0
	s_setprio 1
	v_mfma_f32_16x16x32_bf16 v[122:125], v[162:165], v[188:191], 0
	v_mfma_f32_16x16x32_bf16 v[114:117], v[180:183], v[188:191], 0
	v_mfma_f32_16x16x32_bf16 v[106:109], v[162:165], v[196:199], 0
	v_mfma_f32_16x16x32_bf16 v[98:101], v[180:183], v[196:199], 0
	v_mfma_f32_16x16x32_bf16 v[90:93], v[162:165], v[226:229], 0
	v_mfma_f32_16x16x32_bf16 v[82:85], v[180:183], v[226:229], 0
	v_mfma_f32_16x16x32_bf16 v[74:77], v[162:165], v[234:237], 0
	v_mfma_f32_16x16x32_bf16 v[66:69], v[180:183], v[234:237], 0
	v_mfma_f32_16x16x32_bf16 v[122:125], v[176:179], v[192:195], v[122:125]
	v_mfma_f32_16x16x32_bf16 v[114:117], v[184:187], v[192:195], v[114:117]
	v_mfma_f32_16x16x32_bf16 v[106:109], v[176:179], v[222:225], v[106:109]
	v_mfma_f32_16x16x32_bf16 v[98:101], v[184:187], v[222:225], v[98:101]
	v_mfma_f32_16x16x32_bf16 v[90:93], v[176:179], v[230:233], v[90:93]
	v_mfma_f32_16x16x32_bf16 v[82:85], v[184:187], v[230:233], v[82:85]
	v_mfma_f32_16x16x32_bf16 v[74:77], v[176:179], v[238:241], v[74:77]
	v_mfma_f32_16x16x32_bf16 v[66:69], v[184:187], v[238:241], v[66:69]
	s_setprio 0
	s_barrier
	s_add_i32 s49, s49, s37
	v_lshl_add_u64 v[166:167], s[26:27], 0, v[168:169]
	s_mov_b32 m0, s49
	ds_read_b128 v[188:191], v156 offset:16384
	ds_read_b128 v[192:195], v156 offset:17408
	ds_read_b128 v[196:199], v156 offset:18432
	ds_read_b128 v[222:225], v156 offset:19456
	ds_read_b128 v[226:229], v156 offset:20480
	ds_read_b128 v[230:233], v156 offset:21504
	ds_read_b128 v[234:237], v156 offset:22528
	ds_read_b128 v[238:241], v156 offset:23552
	global_load_lds_dwordx4 v[166:167], off
	s_add_i32 m0, s49, 0x2000
	s_add_u32 s94, s26, 0x80000
	v_lshl_add_u64 v[200:201], s[26:27], 0, v[134:135]
	s_addc_u32 s95, s27, 0
	s_add_i32 s49, s82, s37
	global_load_lds_dwordx4 v[200:201], off
	v_lshl_add_u64 v[242:243], s[94:95], 0, v[168:169]
	s_mov_b32 m0, s49
	v_lshl_add_u64 v[244:245], s[28:29], 0, v[132:133]
	global_load_lds_dwordx4 v[242:243], off
	v_lshl_add_u64 v[242:243], s[94:95], 0, v[134:135]
	s_add_i32 m0, s49, 0x2000
	s_nop 0
	global_load_lds_dwordx4 v[242:243], off
	v_lshl_add_u64 v[242:243], s[28:29], 0, v[130:131]
	s_mov_b32 m0, s38
	s_nop 0
	global_load_lds_dwordx4 v[242:243], off
	s_mov_b32 m0, s39
	s_nop 0
	global_load_lds_dwordx4 v[244:245], off
	s_waitcnt vmcnt(8)
	s_waitcnt lgkmcnt(0)
	s_barrier
; #define PG8_STAGE(bufoff, gbase, voff) do { _Pragma("unroll") for (int _i = 0; _i < 2; ++_i) \
;         __builtin_amdgcn_global_load_lds((const unsigned*)((const char*)(gbase) + (voff)[_i]), (LAS unsigned*)(lds + (bufoff) + ldsw + _i * 8192), 16, 0, 0); } while (0)
; #define PG8_LDA(dst, b, h) do { _Pragma("unroll") for (int m = 0; m < 4; ++m) _Pragma("unroll") for (int k = 0; k < 2; ++k) dst[m][k] = *(const LAS bf16x8*)(lds + PG8_SA(b, h) + aoff + m * 2048 + k * 1024); } while (0)
; #define PG8_LDB(dst, b, h) do { _Pragma("unroll") for (int n = 0; n < 2; ++n) _Pragma("unroll") for (int k = 0; k < 2; ++k) dst[n][k] = *(const LAS bf16x8*)(lds + PG8_SB(b, h) + boff + n * 2048 + k * 1024); } while (0)
; #define PG8_MMA(ai, bj, At, Bt) do { __builtin_amdgcn_s_setprio(1); _Pragma("unroll") for (int m = 0; m < 4; ++m) _Pragma("unroll") for (int n = 0; n < 2; ++n) _Pragma("unroll") for (int k = 0; k < 2; ++k) \
;         acc[ai][bj][m][n] = __builtin_amdgcn_mfma_f32_16x16x32_bf16(Bt[n][k], At[m][k], acc[ai][bj][m][n], 0, 0, 0); __builtin_amdgcn_s_setprio(0); } while (0)
; #define PG8_WAIT_V(n) asm volatile("s_waitcnt vmcnt(" #n ")" ::: "memory")
; #define PG8_WAIT_L(n) asm volatile("s_waitcnt lgkmcnt(" #n ")" ::: "memory")
; #define PG8_BAR __builtin_amdgcn_s_barrier()
; #define PG8_SCHED __builtin_amdgcn_sched_barrier(0)
; template <class Epi>
; __device__ __forceinline__ void gemm_phase(LAS unsigned char* lds, const Sched& S, const Epi& E) {
;     ...
;             PG8_WAIT_V(8); PG8_WAIT_L(0); PG8_BAR; PG8_MMA(1, 0, At, B0); PG8_MMA(1, 1, At, B1); PG8_BAR; PG8_SCHED;
;             PG8_LDB(B0, 1, 0); PG8_LDB(B1, 1, 1); PG8_SCHED; PG8_LDA(At, 1, 0); PG8_STAGE(PG8_SA(0, 1), a2 + hstepA, voffA);
;             PG8_WAIT_V(8); PG8_WAIT_L(0); PG8_BAR; PG8_MMA(0, 0, At, B0); PG8_MMA(0, 1, At, B1); PG8_BAR; PG8_SCHED;
	s_setprio 1
	s_waitcnt lgkmcnt(0)
	v_mfma_f32_16x16x32_bf16 v[62:65], v[140:143], v[188:191], 0
	v_mfma_f32_16x16x32_bf16 v[54:57], v[148:151], v[188:191], 0
	v_mfma_f32_16x16x32_bf16 v[46:49], v[140:143], v[196:199], 0
	v_mfma_f32_16x16x32_bf16 v[38:41], v[148:151], v[196:199], 0
	v_mfma_f32_16x16x32_bf16 v[30:33], v[140:143], v[226:229], 0
	v_mfma_f32_16x16x32_bf16 v[22:25], v[148:151], v[226:229], 0
	v_mfma_f32_16x16x32_bf16 v[14:17], v[140:143], v[234:237], 0
	v_mfma_f32_16x16x32_bf16 v[6:9], v[148:151], v[234:237], 0
	v_mfma_f32_16x16x32_bf16 v[62:65], v[144:147], v[192:195], v[62:65]
	v_mfma_f32_16x16x32_bf16 v[54:57], v[158:161], v[192:195], v[54:57]
	v_mfma_f32_16x16x32_bf16 v[46:49], v[144:147], v[222:225], v[46:49]
	v_mfma_f32_16x16x32_bf16 v[38:41], v[158:161], v[222:225], v[38:41]
	v_mfma_f32_16x16x32_bf16 v[30:33], v[144:147], v[230:233], v[30:33]
	v_mfma_f32_16x16x32_bf16 v[22:25], v[158:161], v[230:233], v[22:25]
	v_mfma_f32_16x16x32_bf16 v[14:17], v[144:147], v[238:241], v[14:17]
	v_mfma_f32_16x16x32_bf16 v[6:9], v[158:161], v[238:241], v[6:9]
	s_setprio 0
	s_setprio 1
	v_mfma_f32_16x16x32_bf16 v[58:61], v[162:165], v[188:191], 0
	v_mfma_f32_16x16x32_bf16 v[50:53], v[180:183], v[188:191], 0
	v_mfma_f32_16x16x32_bf16 v[42:45], v[162:165], v[196:199], 0
	v_mfma_f32_16x16x32_bf16 v[34:37], v[180:183], v[196:199], 0
	v_mfma_f32_16x16x32_bf16 v[26:29], v[162:165], v[226:229], 0
	v_mfma_f32_16x16x32_bf16 v[18:21], v[180:183], v[226:229], 0
	v_mfma_f32_16x16x32_bf16 v[10:13], v[162:165], v[234:237], 0
	v_mfma_f32_16x16x32_bf16 v[2:5], v[180:183], v[234:237], 0
	v_mfma_f32_16x16x32_bf16 v[58:61], v[176:179], v[192:195], v[58:61]
	v_mfma_f32_16x16x32_bf16 v[50:53], v[184:187], v[192:195], v[50:53]
	v_mfma_f32_16x16x32_bf16 v[42:45], v[176:179], v[222:225], v[42:45]
	v_mfma_f32_16x16x32_bf16 v[34:37], v[184:187], v[222:225], v[34:37]
	v_mfma_f32_16x16x32_bf16 v[26:29], v[176:179], v[230:233], v[26:29]
	v_mfma_f32_16x16x32_bf16 v[18:21], v[184:187], v[230:233], v[18:21]
	v_mfma_f32_16x16x32_bf16 v[10:13], v[176:179], v[238:241], v[10:13]
	v_mfma_f32_16x16x32_bf16 v[2:5], v[184:187], v[238:241], v[2:5]
	s_setprio 0
	s_barrier
	s_add_i32 s49, 0, 0x18000
	v_add_u32_e32 v157, s49, v153
	s_add_i32 s82, 0, 0x1c000
	ds_read_b128 v[140:143], v157
	ds_read_b128 v[144:147], v157 offset:1024
	ds_read_b128 v[148:151], v157 offset:2048
	ds_read_b128 v[158:161], v157 offset:3072
	v_add_u32_e32 v157, s82, v153
	ds_read_b128 v[162:165], v157
	ds_read_b128 v[176:179], v157 offset:1024
	ds_read_b128 v[180:183], v157 offset:2048
	ds_read_b128 v[184:187], v157 offset:3072
	s_add_u32 s28, s28, 0x80000
	s_addc_u32 s29, s29, 0
	s_mov_b32 m0, s58
	v_lshl_add_u64 v[246:247], s[28:29], 0, v[130:131]
	ds_read_b128 v[188:191], v156 offset:32768
	ds_read_b128 v[192:195], v156 offset:33792
	ds_read_b128 v[196:199], v156 offset:34816
	ds_read_b128 v[222:225], v156 offset:35840
	ds_read_b128 v[226:229], v156 offset:36864
	ds_read_b128 v[230:233], v156 offset:37888
	ds_read_b128 v[234:237], v156 offset:38912
	ds_read_b128 v[238:241], v156 offset:39936
	global_load_lds_dwordx4 v[246:247], off
	v_lshl_add_u64 v[246:247], s[28:29], 0, v[132:133]
	s_mov_b32 m0, s59
	s_nop 0
	global_load_lds_dwordx4 v[246:247], off
	s_waitcnt vmcnt(8)
	s_waitcnt lgkmcnt(0)
	s_barrier
	s_setprio 1
	s_waitcnt lgkmcnt(0)
	v_mfma_f32_16x16x32_bf16 v[126:129], v[140:143], v[188:191], v[126:129]
	v_mfma_f32_16x16x32_bf16 v[118:121], v[148:151], v[188:191], v[118:121]
	v_mfma_f32_16x16x32_bf16 v[110:113], v[140:143], v[196:199], v[110:113]
	v_mfma_f32_16x16x32_bf16 v[102:105], v[148:151], v[196:199], v[102:105]
	v_mfma_f32_16x16x32_bf16 v[94:97], v[140:143], v[226:229], v[94:97]
	v_mfma_f32_16x16x32_bf16 v[86:89], v[148:151], v[226:229], v[86:89]
	v_mfma_f32_16x16x32_bf16 v[78:81], v[140:143], v[234:237], v[78:81]
	v_mfma_f32_16x16x32_bf16 v[70:73], v[148:151], v[234:237], v[70:73]
	v_mfma_f32_16x16x32_bf16 v[126:129], v[144:147], v[192:195], v[126:129]
	v_mfma_f32_16x16x32_bf16 v[118:121], v[158:161], v[192:195], v[118:121]
	v_mfma_f32_16x16x32_bf16 v[110:113], v[144:147], v[222:225], v[110:113]
	v_mfma_f32_16x16x32_bf16 v[102:105], v[158:161], v[222:225], v[102:105]
	v_mfma_f32_16x16x32_bf16 v[94:97], v[144:147], v[230:233], v[94:97]
	v_mfma_f32_16x16x32_bf16 v[86:89], v[158:161], v[230:233], v[86:89]
	v_mfma_f32_16x16x32_bf16 v[78:81], v[144:147], v[238:241], v[78:81]
	v_mfma_f32_16x16x32_bf16 v[70:73], v[158:161], v[238:241], v[70:73]
	s_setprio 0
	s_setprio 1
	v_mfma_f32_16x16x32_bf16 v[122:125], v[162:165], v[188:191], v[122:125]
	v_mfma_f32_16x16x32_bf16 v[114:117], v[180:183], v[188:191], v[114:117]
	v_mfma_f32_16x16x32_bf16 v[106:109], v[162:165], v[196:199], v[106:109]
	v_mfma_f32_16x16x32_bf16 v[98:101], v[180:183], v[196:199], v[98:101]
	v_mfma_f32_16x16x32_bf16 v[90:93], v[162:165], v[226:229], v[90:93]
	v_mfma_f32_16x16x32_bf16 v[82:85], v[180:183], v[226:229], v[82:85]
	v_mfma_f32_16x16x32_bf16 v[74:77], v[162:165], v[234:237], v[74:77]
	v_mfma_f32_16x16x32_bf16 v[66:69], v[180:183], v[234:237], v[66:69]
	v_mfma_f32_16x16x32_bf16 v[122:125], v[176:179], v[192:195], v[122:125]
	v_mfma_f32_16x16x32_bf16 v[114:117], v[184:187], v[192:195], v[114:117]
	v_mfma_f32_16x16x32_bf16 v[106:109], v[176:179], v[222:225], v[106:109]
	v_mfma_f32_16x16x32_bf16 v[98:101], v[184:187], v[222:225], v[98:101]
	v_mfma_f32_16x16x32_bf16 v[90:93], v[176:179], v[230:233], v[90:93]
	v_mfma_f32_16x16x32_bf16 v[82:85], v[184:187], v[230:233], v[82:85]
	v_mfma_f32_16x16x32_bf16 v[74:77], v[176:179], v[238:241], v[74:77]
	v_mfma_f32_16x16x32_bf16 v[66:69], v[184:187], v[238:241], v[66:69]
	s_setprio 0
	s_barrier
; #define PG8_STAGE(bufoff, gbase, voff) do { _Pragma("unroll") for (int _i = 0; _i < 2; ++_i) \
;         __builtin_amdgcn_global_load_lds((const unsigned*)((const char*)(gbase) + (voff)[_i]), (LAS unsigned*)(lds + (bufoff) + ldsw + _i * 8192), 16, 0, 0); } while (0)
; #define PG8_LDA(dst, b, h) do { _Pragma("unroll") for (int m = 0; m < 4; ++m) _Pragma("unroll") for (int k = 0; k < 2; ++k) dst[m][k] = *(const LAS bf16x8*)(lds + PG8_SA(b, h) + aoff + m * 2048 + k * 1024); } while (0)
; #define PG8_LDB(dst, b, h) do { _Pragma("unroll") for (int n = 0; n < 2; ++n) _Pragma("unroll") for (int k = 0; k < 2; ++k) dst[n][k] = *(const LAS bf16x8*)(lds + PG8_SB(b, h) + boff + n * 2048 + k * 1024); } while (0)
; #define PG8_WAIT_V(n) asm volatile("s_waitcnt vmcnt(" #n ")" ::: "memory")
; #define PG8_WAIT_L(n) asm volatile("s_waitcnt lgkmcnt(" #n ")" ::: "memory")
; template <class Epi>
; __device__ __forceinline__ void gemm_phase(LAS unsigned char* lds, const Sched& S, const Epi& E) {
;     ...
;         for (int t = 0; t < nt; t += 2) {
;             const bool last = (t == nt - 2);
;             const char* a1 = cA + (size_t)(t + 1) * kstep;
;             const char* a2 = last ? nA : cA + (size_t)(t + 2) * kstep; const char* b2 = last ? nB : cB + (size_t)(t + 2) * kstep;
;             const char* a3 = a2 + kstep; const char* b3 = b2 + kstep;
;             PG8_LDB(B0, 0, 0); PG8_LDB(B1, 0, 1); PG8_SCHED; PG8_LDA(At, 0, 0); PG8_STAGE(PG8_SA(1, 1), a1 + hstepA, voffA);
;             PG8_WAIT_V(8); PG8_WAIT_L(0); PG8_BAR; PG8_MMA(0, 0, At, B0); PG8_MMA(0, 1, At, B1); PG8_BAR; PG8_SCHED;
;             PG8_LDA(At, 0, 1); PG8_STAGE(PG8_SB(0, 0), b2, voffB); PG8_STAGE(PG8_SB(0, 1), b2 + hstepB, voffB); PG8_STAGE(PG8_SA(0, 0), a2, voffA);
;             PG8_WAIT_V(8); PG8_WAIT_L(0); PG8_BAR; PG8_MMA(1, 0, At, B0); PG8_MMA(1, 1, At, B1); PG8_BAR; PG8_SCHED;
;             PG8_LDB(B0, 1, 0); PG8_LDB(B1, 1, 1); PG8_SCHED; PG8_LDA(At, 1, 0); PG8_STAGE(PG8_SA(0, 1), a2 + hstepA, voffA);
;             PG8_WAIT_V(8); PG8_WAIT_L(0); PG8_BAR; PG8_MMA(0, 0, At, B0); PG8_MMA(0, 1, At, B1); PG8_BAR; PG8_SCHED;
;             PG8_LDA(At, 1, 1); PG8_STAGE(PG8_SB(1, 0), b3, voffB); PG8_STAGE(PG8_SB(1, 1), b3 + hstepB, voffB); PG8_STAGE(PG8_SA(1, 0), a3, voffA);
;             PG8_WAIT_V(8); PG8_WAIT_L(0); PG8_BAR; PG8_MMA(1, 0, At, B0); PG8_MMA(1, 1, At, B1); PG8_BAR; PG8_SCHED;
;         }
	s_add_i32 s28, s49, s37
	v_lshl_add_u64 v[166:167], v[166:167], 0, s[0:1]
	s_mov_b32 m0, s28
	ds_read_b128 v[188:191], v156 offset:49152
	ds_read_b128 v[192:195], v156 offset:50176
	ds_read_b128 v[196:199], v156 offset:51200
	ds_read_b128 v[222:225], v156 offset:52224
	ds_read_b128 v[226:229], v156 offset:53248
	ds_read_b128 v[230:233], v156 offset:54272
	ds_read_b128 v[234:237], v156 offset:55296
	ds_read_b128 v[238:241], v156 offset:56320
	global_load_lds_dwordx4 v[166:167], off
	s_add_i32 m0, s28, 0x2000
	s_add_u32 s26, s26, 0x80080
	v_lshl_add_u64 v[166:167], v[200:201], 0, s[0:1]
	s_addc_u32 s27, s27, 0
	s_add_i32 s28, s82, s37
	global_load_lds_dwordx4 v[166:167], off
	v_lshl_add_u64 v[166:167], s[26:27], 0, v[168:169]
	s_mov_b32 m0, s28
	s_nop 0
	global_load_lds_dwordx4 v[166:167], off
	v_lshl_add_u64 v[166:167], s[26:27], 0, v[134:135]
	s_add_i32 m0, s28, 0x2000
	s_nop 0
	global_load_lds_dwordx4 v[166:167], off
	v_lshl_add_u64 v[166:167], v[242:243], 0, s[0:1]
	s_mov_b32 m0, s64
	s_nop 0
	global_load_lds_dwordx4 v[166:167], off
	v_lshl_add_u64 v[166:167], v[244:245], 0, s[0:1]
	s_mov_b32 m0, s65
	s_nop 0
	global_load_lds_dwordx4 v[166:167], off
	s_waitcnt vmcnt(8)
	s_waitcnt lgkmcnt(0)
	s_barrier
	s_setprio 1
	s_waitcnt lgkmcnt(0)
	v_mfma_f32_16x16x32_bf16 v[62:65], v[140:143], v[188:191], v[62:65]
	v_mfma_f32_16x16x32_bf16 v[54:57], v[148:151], v[188:191], v[54:57]
	v_mfma_f32_16x16x32_bf16 v[46:49], v[140:143], v[196:199], v[46:49]
	v_mfma_f32_16x16x32_bf16 v[38:41], v[148:151], v[196:199], v[38:41]
	v_mfma_f32_16x16x32_bf16 v[30:33], v[140:143], v[226:229], v[30:33]
	v_mfma_f32_16x16x32_bf16 v[22:25], v[148:151], v[226:229], v[22:25]
	v_mfma_f32_16x16x32_bf16 v[14:17], v[140:143], v[234:237], v[14:17]
	v_mfma_f32_16x16x32_bf16 v[6:9], v[148:151], v[234:237], v[6:9]
	v_mfma_f32_16x16x32_bf16 v[62:65], v[144:147], v[192:195], v[62:65]
	v_mfma_f32_16x16x32_bf16 v[54:57], v[158:161], v[192:195], v[54:57]
	v_mfma_f32_16x16x32_bf16 v[46:49], v[144:147], v[222:225], v[46:49]
	v_mfma_f32_16x16x32_bf16 v[38:41], v[158:161], v[222:225], v[38:41]
	v_mfma_f32_16x16x32_bf16 v[30:33], v[144:147], v[230:233], v[30:33]
	v_mfma_f32_16x16x32_bf16 v[22:25], v[158:161], v[230:233], v[22:25]
	v_mfma_f32_16x16x32_bf16 v[14:17], v[144:147], v[238:241], v[14:17]
	v_mfma_f32_16x16x32_bf16 v[6:9], v[158:161], v[238:241], v[6:9]
	s_setprio 0
	s_setprio 1
	v_mfma_f32_16x16x32_bf16 v[58:61], v[162:165], v[188:191], v[58:61]
	v_mfma_f32_16x16x32_bf16 v[50:53], v[180:183], v[188:191], v[50:53]
	v_mfma_f32_16x16x32_bf16 v[42:45], v[162:165], v[196:199], v[42:45]
	v_mfma_f32_16x16x32_bf16 v[34:37], v[180:183], v[196:199], v[34:37]
	v_mfma_f32_16x16x32_bf16 v[26:29], v[162:165], v[226:229], v[26:29]
	v_mfma_f32_16x16x32_bf16 v[18:21], v[180:183], v[226:229], v[18:21]
	v_mfma_f32_16x16x32_bf16 v[10:13], v[162:165], v[234:237], v[10:13]
	v_mfma_f32_16x16x32_bf16 v[2:5], v[180:183], v[234:237], v[2:5]
	v_mfma_f32_16x16x32_bf16 v[58:61], v[176:179], v[192:195], v[58:61]
	v_mfma_f32_16x16x32_bf16 v[50:53], v[184:187], v[192:195], v[50:53]
	v_mfma_f32_16x16x32_bf16 v[42:45], v[176:179], v[222:225], v[42:45]
	v_mfma_f32_16x16x32_bf16 v[34:37], v[184:187], v[222:225], v[34:37]
	v_mfma_f32_16x16x32_bf16 v[26:29], v[176:179], v[230:233], v[26:29]
	v_mfma_f32_16x16x32_bf16 v[18:21], v[184:187], v[230:233], v[18:21]
	v_mfma_f32_16x16x32_bf16 v[10:13], v[176:179], v[238:241], v[10:13]
	v_mfma_f32_16x16x32_bf16 v[2:5], v[184:187], v[238:241], v[2:5]
	s_setprio 0
	s_barrier
	s_add_i32 s69, s69, 2
	s_add_u32 s24, s24, 0x100
	s_addc_u32 s25, s25, 0
	s_add_u32 s9, s9, 0x100
	s_addc_u32 s11, s11, 0
	s_cmp_gt_u32 s69, 29
	s_cbranch_scc1 .Lpeel_exit_gateup
.LBB0_2278:
	s_add_u32 s26, s24, 0xfff80080
	s_addc_u32 s27, s25, -1
	s_add_i32 s49, 0, 0x10000
	s_cmp_eq_u32 s69, 28
	s_cselect_b32 s29, s19, s27
	s_cselect_b32 s28, s18, s26
	v_add_u32_e32 v157, s49, v153
	s_cselect_b32 s27, s23, s11
	s_cselect_b32 s26, s22, s9
	s_add_i32 s82, 0, 0x14000
	ds_read_b128 v[140:143], v157
	ds_read_b128 v[144:147], v157 offset:1024
	ds_read_b128 v[148:151], v157 offset:2048
	ds_read_b128 v[158:161], v157 offset:3072
	v_add_u32_e32 v157, s82, v153
	ds_read_b128 v[162:165], v157
	ds_read_b128 v[176:179], v157 offset:1024
	ds_read_b128 v[180:183], v157 offset:2048
	ds_read_b128 v[184:187], v157 offset:3072
	v_lshl_add_u64 v[166:167], s[24:25], 0, v[136:137]
	s_add_i32 m0, s38, 0xc000
	ds_read_b128 v[188:191], v156
	ds_read_b128 v[192:195], v156 offset:1024
	ds_read_b128 v[196:199], v156 offset:2048
	ds_read_b128 v[222:225], v156 offset:3072
	ds_read_b128 v[226:229], v156 offset:4096
	ds_read_b128 v[230:233], v156 offset:5120
	ds_read_b128 v[234:237], v156 offset:6144
	ds_read_b128 v[238:241], v156 offset:7168
	global_load_lds_dwordx4 v[166:167], off
	v_lshl_add_u64 v[166:167], s[24:25], 0, v[138:139]
	s_add_i32 m0, s38, 0xe000
	s_nop 0
	global_load_lds_dwordx4 v[166:167], off
	s_waitcnt vmcnt(8)
	s_waitcnt lgkmcnt(0)
	s_barrier
; #define PG8_STAGE(bufoff, gbase, voff) do { _Pragma("unroll") for (int _i = 0; _i < 2; ++_i) \
;         __builtin_amdgcn_global_load_lds((const unsigned*)((const char*)(gbase) + (voff)[_i]), (LAS unsigned*)(lds + (bufoff) + ldsw + _i * 8192), 16, 0, 0); } while (0)
; #define PG8_LDA(dst, b, h) do { _Pragma("unroll") for (int m = 0; m < 4; ++m) _Pragma("unroll") for (int k = 0; k < 2; ++k) dst[m][k] = *(const LAS bf16x8*)(lds + PG8_SA(b, h) + aoff + m * 2048 + k * 1024); } while (0)
; #define PG8_MMA(ai, bj, At, Bt) do { __builtin_amdgcn_s_setprio(1); _Pragma("unroll") for (int m = 0; m < 4; ++m) _Pragma("unroll") for (int n = 0; n < 2; ++n) _Pragma("unroll") for (int k = 0; k < 2; ++k) \
;         acc[ai][bj][m][n] = __builtin_amdgcn_mfma_f32_16x16x32_bf16(Bt[n][k], At[m][k], acc[ai][bj][m][n], 0, 0, 0); __builtin_amdgcn_s_setprio(0); } while (0)
; #define PG8_WAIT_V(n) asm volatile("s_waitcnt vmcnt(" #n ")" ::: "memory")
; #define PG8_WAIT_L(n) asm volatile("s_waitcnt lgkmcnt(" #n ")" ::: "memory")
; #define PG8_BAR __builtin_amdgcn_s_barrier()
; #define PG8_SCHED __builtin_amdgcn_sched_barrier(0)
; template <class Epi>
; __device__ __forceinline__ void gemm_phase(LAS unsigned char* lds, const Sched& S, const Epi& E) {
;     ...
;             PG8_WAIT_V(8); PG8_WAIT_L(0); PG8_BAR; PG8_MMA(0, 0, At, B0); PG8_MMA(0, 1, At, B1); PG8_BAR; PG8_SCHED;
;             PG8_LDA(At, 0, 1); PG8_STAGE(PG8_SB(0, 0), b2, voffB); PG8_STAGE(PG8_SB(0, 1), b2 + hstepB, voffB); PG8_STAGE(PG8_SA(0, 0), a2, voffA);
;             PG8_WAIT_V(8); PG8_WAIT_L(0); PG8_BAR; PG8_MMA(1, 0, At, B0); PG8_MMA(1, 1, At, B1); PG8_BAR; PG8_SCHED;
	s_setprio 1
	s_waitcnt lgkmcnt(0)
	v_mfma_f32_16x16x32_bf16 v[126:129], v[140:143], v[188:191], v[126:129]
	v_mfma_f32_16x16x32_bf16 v[118:121], v[148:151], v[188:191], v[118:121]
	v_mfma_f32_16x16x32_bf16 v[110:113], v[140:143], v[196:199], v[110:113]
	v_mfma_f32_16x16x32_bf16 v[102:105], v[148:151], v[196:199], v[102:105]
	v_mfma_f32_16x16x32_bf16 v[94:97], v[140:143], v[226:229], v[94:97]
	v_mfma_f32_16x16x32_bf16 v[86:89], v[148:151], v[226:229], v[86:89]
	v_mfma_f32_16x16x32_bf16 v[78:81], v[140:143], v[234:237], v[78:81]
	v_mfma_f32_16x16x32_bf16 v[70:73], v[148:151], v[234:237], v[70:73]
	v_mfma_f32_16x16x32_bf16 v[126:129], v[144:147], v[192:195], v[126:129]
	v_mfma_f32_16x16x32_bf16 v[118:121], v[158:161], v[192:195], v[118:121]
	v_mfma_f32_16x16x32_bf16 v[110:113], v[144:147], v[222:225], v[110:113]
	v_mfma_f32_16x16x32_bf16 v[102:105], v[158:161], v[222:225], v[102:105]
	v_mfma_f32_16x16x32_bf16 v[94:97], v[144:147], v[230:233], v[94:97]
	v_mfma_f32_16x16x32_bf16 v[86:89], v[158:161], v[230:233], v[86:89]
	v_mfma_f32_16x16x32_bf16 v[78:81], v[144:147], v[238:241], v[78:81]
	v_mfma_f32_16x16x32_bf16 v[70:73], v[158:161], v[238:241], v[70:73]
	s_setprio 0
	s_setprio 1
	v_mfma_f32_16x16x32_bf16 v[122:125], v[162:165], v[188:191], v[122:125]
	v_mfma_f32_16x16x32_bf16 v[114:117], v[180:183], v[188:191], v[114:117]
	v_mfma_f32_16x16x32_bf16 v[106:109], v[162:165], v[196:199], v[106:109]
	v_mfma_f32_16x16x32_bf16 v[98:101], v[180:183], v[196:199], v[98:101]
	v_mfma_f32_16x16x32_bf16 v[90:93], v[162:165], v[226:229], v[90:93]
	v_mfma_f32_16x16x32_bf16 v[82:85], v[180:183], v[226:229], v[82:85]
	v_mfma_f32_16x16x32_bf16 v[74:77], v[162:165], v[234:237], v[74:77]
	v_mfma_f32_16x16x32_bf16 v[66:69], v[180:183], v[234:237], v[66:69]
	v_mfma_f32_16x16x32_bf16 v[122:125], v[176:179], v[192:195], v[122:125]
	v_mfma_f32_16x16x32_bf16 v[114:117], v[184:187], v[192:195], v[114:117]
	v_mfma_f32_16x16x32_bf16 v[106:109], v[176:179], v[222:225], v[106:109]
	v_mfma_f32_16x16x32_bf16 v[98:101], v[184:187], v[222:225], v[98:101]
	v_mfma_f32_16x16x32_bf16 v[90:93], v[176:179], v[230:233], v[90:93]
	v_mfma_f32_16x16x32_bf16 v[82:85], v[184:187], v[230:233], v[82:85]
	v_mfma_f32_16x16x32_bf16 v[74:77], v[176:179], v[238:241], v[74:77]
	v_mfma_f32_16x16x32_bf16 v[66:69], v[184:187], v[238:241], v[66:69]
	s_setprio 0
	s_barrier
	s_add_i32 s49, s49, s37
	v_lshl_add_u64 v[166:167], s[26:27], 0, v[168:169]
	s_mov_b32 m0, s49
	ds_read_b128 v[188:191], v156 offset:16384
	ds_read_b128 v[192:195], v156 offset:17408
	ds_read_b128 v[196:199], v156 offset:18432
	ds_read_b128 v[222:225], v156 offset:19456
	ds_read_b128 v[226:229], v156 offset:20480
	ds_read_b128 v[230:233], v156 offset:21504
	ds_read_b128 v[234:237], v156 offset:22528
	ds_read_b128 v[238:241], v156 offset:23552
	global_load_lds_dwordx4 v[166:167], off
	s_add_i32 m0, s49, 0x2000
	s_add_u32 s94, s26, 0x80000
	v_lshl_add_u64 v[200:201], s[26:27], 0, v[134:135]
	s_addc_u32 s95, s27, 0
	s_add_i32 s49, s82, s37
	global_load_lds_dwordx4 v[200:201], off
	v_lshl_add_u64 v[242:243], s[94:95], 0, v[168:169]
	s_mov_b32 m0, s49
	v_lshl_add_u64 v[244:245], s[28:29], 0, v[132:133]
	global_load_lds_dwordx4 v[242:243], off
	v_lshl_add_u64 v[242:243], s[94:95], 0, v[134:135]
	s_add_i32 m0, s49, 0x2000
	s_nop 0
	global_load_lds_dwordx4 v[242:243], off
	v_lshl_add_u64 v[242:243], s[28:29], 0, v[130:131]
	s_mov_b32 m0, s38
	s_nop 0
	global_load_lds_dwordx4 v[242:243], off
	s_mov_b32 m0, s39
	s_nop 0
	global_load_lds_dwordx4 v[244:245], off
	s_waitcnt vmcnt(8)
	s_waitcnt lgkmcnt(0)
	s_barrier
	s_setprio 1
	s_waitcnt lgkmcnt(0)
	v_mfma_f32_16x16x32_bf16 v[62:65], v[140:143], v[188:191], v[62:65]
	v_mfma_f32_16x16x32_bf16 v[54:57], v[148:151], v[188:191], v[54:57]
	v_mfma_f32_16x16x32_bf16 v[46:49], v[140:143], v[196:199], v[46:49]
	v_mfma_f32_16x16x32_bf16 v[38:41], v[148:151], v[196:199], v[38:41]
	v_mfma_f32_16x16x32_bf16 v[30:33], v[140:143], v[226:229], v[30:33]
	v_mfma_f32_16x16x32_bf16 v[22:25], v[148:151], v[226:229], v[22:25]
	v_mfma_f32_16x16x32_bf16 v[14:17], v[140:143], v[234:237], v[14:17]
	v_mfma_f32_16x16x32_bf16 v[6:9], v[148:151], v[234:237], v[6:9]
	v_mfma_f32_16x16x32_bf16 v[62:65], v[144:147], v[192:195], v[62:65]
	v_mfma_f32_16x16x32_bf16 v[54:57], v[158:161], v[192:195], v[54:57]
	v_mfma_f32_16x16x32_bf16 v[46:49], v[144:147], v[222:225], v[46:49]
	v_mfma_f32_16x16x32_bf16 v[38:41], v[158:161], v[222:225], v[38:41]
	v_mfma_f32_16x16x32_bf16 v[30:33], v[144:147], v[230:233], v[30:33]
	v_mfma_f32_16x16x32_bf16 v[22:25], v[158:161], v[230:233], v[22:25]
	v_mfma_f32_16x16x32_bf16 v[14:17], v[144:147], v[238:241], v[14:17]
	v_mfma_f32_16x16x32_bf16 v[6:9], v[158:161], v[238:241], v[6:9]
	s_setprio 0
	s_setprio 1
	v_mfma_f32_16x16x32_bf16 v[58:61], v[162:165], v[188:191], v[58:61]
	v_mfma_f32_16x16x32_bf16 v[50:53], v[180:183], v[188:191], v[50:53]
	v_mfma_f32_16x16x32_bf16 v[42:45], v[162:165], v[196:199], v[42:45]
	v_mfma_f32_16x16x32_bf16 v[34:37], v[180:183], v[196:199], v[34:37]
	v_mfma_f32_16x16x32_bf16 v[26:29], v[162:165], v[226:229], v[26:29]
	v_mfma_f32_16x16x32_bf16 v[18:21], v[180:183], v[226:229], v[18:21]
	v_mfma_f32_16x16x32_bf16 v[10:13], v[162:165], v[234:237], v[10:13]
	v_mfma_f32_16x16x32_bf16 v[2:5], v[180:183], v[234:237], v[2:5]
	v_mfma_f32_16x16x32_bf16 v[58:61], v[176:179], v[192:195], v[58:61]
	v_mfma_f32_16x16x32_bf16 v[50:53], v[184:187], v[192:195], v[50:53]
	v_mfma_f32_16x16x32_bf16 v[42:45], v[176:179], v[222:225], v[42:45]
	v_mfma_f32_16x16x32_bf16 v[34:37], v[184:187], v[222:225], v[34:37]
	v_mfma_f32_16x16x32_bf16 v[26:29], v[176:179], v[230:233], v[26:29]
	v_mfma_f32_16x16x32_bf16 v[18:21], v[184:187], v[230:233], v[18:21]
	v_mfma_f32_16x16x32_bf16 v[10:13], v[176:179], v[238:241], v[10:13]
	v_mfma_f32_16x16x32_bf16 v[2:5], v[184:187], v[238:241], v[2:5]
	s_setprio 0
	s_barrier
; #define PG8_STAGE(bufoff, gbase, voff) do { _Pragma("unroll") for (int _i = 0; _i < 2; ++_i) \
;         __builtin_amdgcn_global_load_lds((const unsigned*)((const char*)(gbase) + (voff)[_i]), (LAS unsigned*)(lds + (bufoff) + ldsw + _i * 8192), 16, 0, 0); } while (0)
; #define PG8_LDA(dst, b, h) do { _Pragma("unroll") for (int m = 0; m < 4; ++m) _Pragma("unroll") for (int k = 0; k < 2; ++k) dst[m][k] = *(const LAS bf16x8*)(lds + PG8_SA(b, h) + aoff + m * 2048 + k * 1024); } while (0)
; #define PG8_LDB(dst, b, h) do { _Pragma("unroll") for (int n = 0; n < 2; ++n) _Pragma("unroll") for (int k = 0; k < 2; ++k) dst[n][k] = *(const LAS bf16x8*)(lds + PG8_SB(b, h) + boff + n * 2048 + k * 1024); } while (0)
; #define PG8_MMA(ai, bj, At, Bt) do { __builtin_amdgcn_s_setprio(1); _Pragma("unroll") for (int m = 0; m < 4; ++m) _Pragma("unroll") for (int n = 0; n < 2; ++n) _Pragma("unroll") for (int k = 0; k < 2; ++k) \
;         acc[ai][bj][m][n] = __builtin_amdgcn_mfma_f32_16x16x32_bf16(Bt[n][k], At[m][k], acc[ai][bj][m][n], 0, 0, 0); __builtin_amdgcn_s_setprio(0); } while (0)
; #define PG8_WAIT_V(n) asm volatile("s_waitcnt vmcnt(" #n ")" ::: "memory")
; #define PG8_WAIT_L(n) asm volatile("s_waitcnt lgkmcnt(" #n ")" ::: "memory")
; #define PG8_BAR __builtin_amdgcn_s_barrier()
; #define PG8_SCHED __builtin_amdgcn_sched_barrier(0)
; template <class Epi>
; __device__ __forceinline__ void gemm_phase(LAS unsigned char* lds, const Sched& S, const Epi& E) {
;     ...
;             PG8_LDB(B0, 1, 0); PG8_LDB(B1, 1, 1); PG8_SCHED; PG8_LDA(At, 1, 0); PG8_STAGE(PG8_SA(0, 1), a2 + hstepA, voffA);
;             PG8_WAIT_V(8); PG8_WAIT_L(0); PG8_BAR; PG8_MMA(0, 0, At, B0); PG8_MMA(0, 1, At, B1); PG8_BAR; PG8_SCHED;
;             PG8_LDA(At, 1, 1); PG8_STAGE(PG8_SB(1, 0), b3, voffB); PG8_STAGE(PG8_SB(1, 1), b3 + hstepB, voffB); PG8_STAGE(PG8_SA(1, 0), a3, voffA);
;             PG8_WAIT_V(8); PG8_WAIT_L(0); PG8_BAR; PG8_MMA(1, 0, At, B0); PG8_MMA(1, 1, At, B1); PG8_BAR; PG8_SCHED;
	s_add_i32 s49, 0, 0x18000
	v_add_u32_e32 v157, s49, v153
	s_add_i32 s82, 0, 0x1c000
	ds_read_b128 v[140:143], v157
	ds_read_b128 v[144:147], v157 offset:1024
	ds_read_b128 v[148:151], v157 offset:2048
	ds_read_b128 v[158:161], v157 offset:3072
	v_add_u32_e32 v157, s82, v153
	ds_read_b128 v[162:165], v157
	ds_read_b128 v[176:179], v157 offset:1024
	ds_read_b128 v[180:183], v157 offset:2048
	ds_read_b128 v[184:187], v157 offset:3072
	s_add_u32 s28, s28, 0x80000
	s_addc_u32 s29, s29, 0
	s_mov_b32 m0, s58
	v_lshl_add_u64 v[246:247], s[28:29], 0, v[130:131]
	ds_read_b128 v[188:191], v156 offset:32768
	ds_read_b128 v[192:195], v156 offset:33792
	ds_read_b128 v[196:199], v156 offset:34816
	ds_read_b128 v[222:225], v156 offset:35840
	ds_read_b128 v[226:229], v156 offset:36864
	ds_read_b128 v[230:233], v156 offset:37888
	ds_read_b128 v[234:237], v156 offset:38912
	ds_read_b128 v[238:241], v156 offset:39936
	global_load_lds_dwordx4 v[246:247], off
	v_lshl_add_u64 v[246:247], s[28:29], 0, v[132:133]
	s_mov_b32 m0, s59
	s_nop 0
	global_load_lds_dwordx4 v[246:247], off
	s_waitcnt vmcnt(8)
	s_waitcnt lgkmcnt(0)
	s_barrier
	s_setprio 1
	s_waitcnt lgkmcnt(0)
	v_mfma_f32_16x16x32_bf16 v[126:129], v[140:143], v[188:191], v[126:129]
	v_mfma_f32_16x16x32_bf16 v[118:121], v[148:151], v[188:191], v[118:121]
	v_mfma_f32_16x16x32_bf16 v[110:113], v[140:143], v[196:199], v[110:113]
	v_mfma_f32_16x16x32_bf16 v[102:105], v[148:151], v[196:199], v[102:105]
	v_mfma_f32_16x16x32_bf16 v[94:97], v[140:143], v[226:229], v[94:97]
	v_mfma_f32_16x16x32_bf16 v[86:89], v[148:151], v[226:229], v[86:89]
	v_mfma_f32_16x16x32_bf16 v[78:81], v[140:143], v[234:237], v[78:81]
	v_mfma_f32_16x16x32_bf16 v[70:73], v[148:151], v[234:237], v[70:73]
	v_mfma_f32_16x16x32_bf16 v[126:129], v[144:147], v[192:195], v[126:129]
	v_mfma_f32_16x16x32_bf16 v[118:121], v[158:161], v[192:195], v[118:121]
	v_mfma_f32_16x16x32_bf16 v[110:113], v[144:147], v[222:225], v[110:113]
	v_mfma_f32_16x16x32_bf16 v[102:105], v[158:161], v[222:225], v[102:105]
	v_mfma_f32_16x16x32_bf16 v[94:97], v[144:147], v[230:233], v[94:97]
	v_mfma_f32_16x16x32_bf16 v[86:89], v[158:161], v[230:233], v[86:89]
	v_mfma_f32_16x16x32_bf16 v[78:81], v[144:147], v[238:241], v[78:81]
	v_mfma_f32_16x16x32_bf16 v[70:73], v[158:161], v[238:241], v[70:73]
	s_setprio 0
	s_setprio 1
	v_mfma_f32_16x16x32_bf16 v[122:125], v[162:165], v[188:191], v[122:125]
	v_mfma_f32_16x16x32_bf16 v[114:117], v[180:183], v[188:191], v[114:117]
	v_mfma_f32_16x16x32_bf16 v[106:109], v[162:165], v[196:199], v[106:109]
	v_mfma_f32_16x16x32_bf16 v[98:101], v[180:183], v[196:199], v[98:101]
	v_mfma_f32_16x16x32_bf16 v[90:93], v[162:165], v[226:229], v[90:93]
	v_mfma_f32_16x16x32_bf16 v[82:85], v[180:183], v[226:229], v[82:85]
	v_mfma_f32_16x16x32_bf16 v[74:77], v[162:165], v[234:237], v[74:77]
	v_mfma_f32_16x16x32_bf16 v[66:69], v[180:183], v[234:237], v[66:69]
	v_mfma_f32_16x16x32_bf16 v[122:125], v[176:179], v[192:195], v[122:125]
	v_mfma_f32_16x16x32_bf16 v[114:117], v[184:187], v[192:195], v[114:117]
	v_mfma_f32_16x16x32_bf16 v[106:109], v[176:179], v[222:225], v[106:109]
	v_mfma_f32_16x16x32_bf16 v[98:101], v[184:187], v[222:225], v[98:101]
	v_mfma_f32_16x16x32_bf16 v[90:93], v[176:179], v[230:233], v[90:93]
	v_mfma_f32_16x16x32_bf16 v[82:85], v[184:187], v[230:233], v[82:85]
	v_mfma_f32_16x16x32_bf16 v[74:77], v[176:179], v[238:241], v[74:77]
	v_mfma_f32_16x16x32_bf16 v[66:69], v[184:187], v[238:241], v[66:69]
	s_setprio 0
	s_barrier
	s_add_i32 s28, s49, s37
	v_lshl_add_u64 v[166:167], v[166:167], 0, s[0:1]
	s_mov_b32 m0, s28
	ds_read_b128 v[188:191], v156 offset:49152
	ds_read_b128 v[192:195], v156 offset:50176
	ds_read_b128 v[196:199], v156 offset:51200
	ds_read_b128 v[222:225], v156 offset:52224
	ds_read_b128 v[226:229], v156 offset:53248
	ds_read_b128 v[230:233], v156 offset:54272
	ds_read_b128 v[234:237], v156 offset:55296
	ds_read_b128 v[238:241], v156 offset:56320
	global_load_lds_dwordx4 v[166:167], off
	s_add_i32 m0, s28, 0x2000
	s_add_u32 s26, s26, 0x80080
	v_lshl_add_u64 v[166:167], v[200:201], 0, s[0:1]
	s_addc_u32 s27, s27, 0
	s_add_i32 s28, s82, s37
	global_load_lds_dwordx4 v[166:167], off
	v_lshl_add_u64 v[166:167], s[26:27], 0, v[168:169]
	s_mov_b32 m0, s28
	s_nop 0
	global_load_lds_dwordx4 v[166:167], off
	v_lshl_add_u64 v[166:167], s[26:27], 0, v[134:135]
	s_add_i32 m0, s28, 0x2000
	s_nop 0
	global_load_lds_dwordx4 v[166:167], off
	v_lshl_add_u64 v[166:167], v[242:243], 0, s[0:1]
	s_mov_b32 m0, s64
	s_nop 0
	global_load_lds_dwordx4 v[166:167], off
	v_lshl_add_u64 v[166:167], v[244:245], 0, s[0:1]
	s_mov_b32 m0, s65
	s_nop 0
	global_load_lds_dwordx4 v[166:167], off
	s_waitcnt vmcnt(8)
	s_waitcnt lgkmcnt(0)
	s_barrier
; #define PG8_STAGE(bufoff, gbase, voff) do { _Pragma("unroll") for (int _i = 0; _i < 2; ++_i) \
;         __builtin_amdgcn_global_load_lds((const unsigned*)((const char*)(gbase) + (voff)[_i]), (LAS unsigned*)(lds + (bufoff) + ldsw + _i * 8192), 16, 0, 0); } while (0)
; #define PG8_LDA(dst, b, h) do { _Pragma("unroll") for (int m = 0; m < 4; ++m) _Pragma("unroll") for (int k = 0; k < 2; ++k) dst[m][k] = *(const LAS bf16x8*)(lds + PG8_SA(b, h) + aoff + m * 2048 + k * 1024); } while (0)
; #define PG8_LDB(dst, b, h) do { _Pragma("unroll") for (int n = 0; n < 2; ++n) _Pragma("unroll") for (int k = 0; k < 2; ++k) dst[n][k] = *(const LAS bf16x8*)(lds + PG8_SB(b, h) + boff + n * 2048 + k * 1024); } while (0)
; #define PG8_WAIT_V(n) asm volatile("s_waitcnt vmcnt(" #n ")" ::: "memory")
; #define PG8_WAIT_L(n) asm volatile("s_waitcnt lgkmcnt(" #n ")" ::: "memory")
; template <class Epi>
; __device__ __forceinline__ void gemm_phase(LAS unsigned char* lds, const Sched& S, const Epi& E) {
;     ...
;         for (int t = 0; t < nt; t += 2) {
;             const bool last = (t == nt - 2);
;             const char* a1 = cA + (size_t)(t + 1) * kstep;
;             const char* a2 = last ? nA : cA + (size_t)(t + 2) * kstep; const char* b2 = last ? nB : cB + (size_t)(t + 2) * kstep;
;             const char* a3 = a2 + kstep; const char* b3 = b2 + kstep;
;             PG8_LDB(B0, 0, 0); PG8_LDB(B1, 0, 1); PG8_SCHED; PG8_LDA(At, 0, 0); PG8_STAGE(PG8_SA(1, 1), a1 + hstepA, voffA);
;             PG8_WAIT_V(8); PG8_WAIT_L(0); PG8_BAR; PG8_MMA(0, 0, At, B0); PG8_MMA(0, 1, At, B1); PG8_BAR; PG8_SCHED;
;             PG8_LDA(At, 0, 1); PG8_STAGE(PG8_SB(0, 0), b2, voffB); PG8_STAGE(PG8_SB(0, 1), b2 + hstepB, voffB); PG8_STAGE(PG8_SA(0, 0), a2, voffA);
;             PG8_WAIT_V(8); PG8_WAIT_L(0); PG8_BAR; PG8_MMA(1, 0, At, B0); PG8_MMA(1, 1, At, B1); PG8_BAR; PG8_SCHED;
;             PG8_LDB(B0, 1, 0); PG8_LDB(B1, 1, 1); PG8_SCHED; PG8_LDA(At, 1, 0); PG8_STAGE(PG8_SA(0, 1), a2 + hstepA, voffA);
;             PG8_WAIT_V(8); PG8_WAIT_L(0); PG8_BAR; PG8_MMA(0, 0, At, B0); PG8_MMA(0, 1, At, B1); PG8_BAR; PG8_SCHED;
;             PG8_LDA(At, 1, 1); PG8_STAGE(PG8_SB(1, 0), b3, voffB); PG8_STAGE(PG8_SB(1, 1), b3 + hstepB, voffB); PG8_STAGE(PG8_SA(1, 0), a3, voffA);
;             PG8_WAIT_V(8); PG8_WAIT_L(0); PG8_BAR; PG8_MMA(1, 0, At, B0); PG8_MMA(1, 1, At, B1); PG8_BAR; PG8_SCHED;
;         }
	s_setprio 1
	s_waitcnt lgkmcnt(0)
	v_mfma_f32_16x16x32_bf16 v[62:65], v[140:143], v[188:191], v[62:65]
	v_mfma_f32_16x16x32_bf16 v[54:57], v[148:151], v[188:191], v[54:57]
	v_mfma_f32_16x16x32_bf16 v[46:49], v[140:143], v[196:199], v[46:49]
	v_mfma_f32_16x16x32_bf16 v[38:41], v[148:151], v[196:199], v[38:41]
	v_mfma_f32_16x16x32_bf16 v[30:33], v[140:143], v[226:229], v[30:33]
	v_mfma_f32_16x16x32_bf16 v[22:25], v[148:151], v[226:229], v[22:25]
	v_mfma_f32_16x16x32_bf16 v[14:17], v[140:143], v[234:237], v[14:17]
	v_mfma_f32_16x16x32_bf16 v[6:9], v[148:151], v[234:237], v[6:9]
	v_mfma_f32_16x16x32_bf16 v[62:65], v[144:147], v[192:195], v[62:65]
	v_mfma_f32_16x16x32_bf16 v[54:57], v[158:161], v[192:195], v[54:57]
	v_mfma_f32_16x16x32_bf16 v[46:49], v[144:147], v[222:225], v[46:49]
	v_mfma_f32_16x16x32_bf16 v[38:41], v[158:161], v[222:225], v[38:41]
	v_mfma_f32_16x16x32_bf16 v[30:33], v[144:147], v[230:233], v[30:33]
	v_mfma_f32_16x16x32_bf16 v[22:25], v[158:161], v[230:233], v[22:25]
	v_mfma_f32_16x16x32_bf16 v[14:17], v[144:147], v[238:241], v[14:17]
	v_mfma_f32_16x16x32_bf16 v[6:9], v[158:161], v[238:241], v[6:9]
	s_setprio 0
	s_setprio 1
	v_mfma_f32_16x16x32_bf16 v[58:61], v[162:165], v[188:191], v[58:61]
	v_mfma_f32_16x16x32_bf16 v[50:53], v[180:183], v[188:191], v[50:53]
	v_mfma_f32_16x16x32_bf16 v[42:45], v[162:165], v[196:199], v[42:45]
	v_mfma_f32_16x16x32_bf16 v[34:37], v[180:183], v[196:199], v[34:37]
	v_mfma_f32_16x16x32_bf16 v[26:29], v[162:165], v[226:229], v[26:29]
	v_mfma_f32_16x16x32_bf16 v[18:21], v[180:183], v[226:229], v[18:21]
	v_mfma_f32_16x16x32_bf16 v[10:13], v[162:165], v[234:237], v[10:13]
	v_mfma_f32_16x16x32_bf16 v[2:5], v[180:183], v[234:237], v[2:5]
	v_mfma_f32_16x16x32_bf16 v[58:61], v[176:179], v[192:195], v[58:61]
	v_mfma_f32_16x16x32_bf16 v[50:53], v[184:187], v[192:195], v[50:53]
	v_mfma_f32_16x16x32_bf16 v[42:45], v[176:179], v[222:225], v[42:45]
	v_mfma_f32_16x16x32_bf16 v[34:37], v[184:187], v[222:225], v[34:37]
	v_mfma_f32_16x16x32_bf16 v[26:29], v[176:179], v[230:233], v[26:29]
	v_mfma_f32_16x16x32_bf16 v[18:21], v[184:187], v[230:233], v[18:21]
	v_mfma_f32_16x16x32_bf16 v[10:13], v[176:179], v[238:241], v[10:13]
	v_mfma_f32_16x16x32_bf16 v[2:5], v[184:187], v[238:241], v[2:5]
	s_setprio 0
	s_barrier
	s_add_i32 s69, s69, 2
	s_add_u32 s24, s24, 0x100
	s_addc_u32 s25, s25, 0
	s_add_u32 s9, s9, 0x100
	s_addc_u32 s11, s11, 0
	s_cmp_gt_u32 s69, 29
	s_cbranch_scc0 .LBB0_2278
	s_branch .Lpeel_exit_gateup
.Ltail_peel_gateup:
	s_add_u32 s26, s24, 0xfff80080
	s_addc_u32 s27, s25, -1
	s_add_i32 s49, 0, 0x10000
	s_cmp_eq_u32 s69, 28
	s_cselect_b32 s29, s19, s27
	s_cselect_b32 s28, s18, s26
	v_add_u32_e32 v157, s49, v153
	s_cselect_b32 s27, s23, s11
	s_cselect_b32 s26, s22, s9
	s_add_i32 s82, 0, 0x14000
	ds_read_b128 v[140:143], v157
	ds_read_b128 v[144:147], v157 offset:1024
	ds_read_b128 v[148:151], v157 offset:2048
	ds_read_b128 v[158:161], v157 offset:3072
	v_add_u32_e32 v157, s82, v153
	ds_read_b128 v[162:165], v157
	ds_read_b128 v[176:179], v157 offset:1024
	ds_read_b128 v[180:183], v157 offset:2048
	ds_read_b128 v[184:187], v157 offset:3072
	v_lshl_add_u64 v[166:167], s[24:25], 0, v[136:137]
	s_add_i32 m0, s38, 0xc000
	ds_read_b128 v[188:191], v156
	ds_read_b128 v[192:195], v156 offset:1024
	ds_read_b128 v[196:199], v156 offset:2048
	ds_read_b128 v[222:225], v156 offset:3072
	ds_read_b128 v[226:229], v156 offset:4096
	ds_read_b128 v[230:233], v156 offset:5120
	ds_read_b128 v[234:237], v156 offset:6144
	ds_read_b128 v[238:241], v156 offset:7168
	global_load_lds_dwordx4 v[166:167], off
	v_lshl_add_u64 v[166:167], s[24:25], 0, v[138:139]
	s_add_i32 m0, s38, 0xe000
	s_nop 0
	global_load_lds_dwordx4 v[166:167], off
	s_waitcnt vmcnt(8)
	s_waitcnt lgkmcnt(0)
	s_barrier
	s_setprio 1
	s_waitcnt lgkmcnt(0)
	s_cmp_eq_u64 s[6:7], 0
	s_cbranch_scc1 .Ltskip_gateupp_0
	v_mfma_f32_16x16x32_bf16 v[126:129], v[140:143], v[188:191], 0
	v_mfma_f32_16x16x32_bf16 v[118:121], v[148:151], v[188:191], 0
	v_mfma_f32_16x16x32_bf16 v[110:113], v[140:143], v[196:199], 0
	v_mfma_f32_16x16x32_bf16 v[102:105], v[148:151], v[196:199], 0
	v_mfma_f32_16x16x32_bf16 v[94:97], v[140:143], v[226:229], 0
	v_mfma_f32_16x16x32_bf16 v[86:89], v[148:151], v[226:229], 0
	v_mfma_f32_16x16x32_bf16 v[78:81], v[140:143], v[234:237], 0
	v_mfma_f32_16x16x32_bf16 v[70:73], v[148:151], v[234:237], 0
	v_mfma_f32_16x16x32_bf16 v[126:129], v[144:147], v[192:195], v[126:129]
	v_mfma_f32_16x16x32_bf16 v[118:121], v[158:161], v[192:195], v[118:121]
	v_mfma_f32_16x16x32_bf16 v[110:113], v[144:147], v[222:225], v[110:113]
	v_mfma_f32_16x16x32_bf16 v[102:105], v[158:161], v[222:225], v[102:105]
	v_mfma_f32_16x16x32_bf16 v[94:97], v[144:147], v[230:233], v[94:97]
	v_mfma_f32_16x16x32_bf16 v[86:89], v[158:161], v[230:233], v[86:89]
	v_mfma_f32_16x16x32_bf16 v[78:81], v[144:147], v[238:241], v[78:81]
	v_mfma_f32_16x16x32_bf16 v[70:73], v[158:161], v[238:241], v[70:73]
	s_setprio 0
	s_setprio 1
	v_mfma_f32_16x16x32_bf16 v[122:125], v[162:165], v[188:191], 0
	v_mfma_f32_16x16x32_bf16 v[114:117], v[180:183], v[188:191], 0
	v_mfma_f32_16x16x32_bf16 v[106:109], v[162:165], v[196:199], 0
	v_mfma_f32_16x16x32_bf16 v[98:101], v[180:183], v[196:199], 0
	v_mfma_f32_16x16x32_bf16 v[90:93], v[162:165], v[226:229], 0
	v_mfma_f32_16x16x32_bf16 v[82:85], v[180:183], v[226:229], 0
	v_mfma_f32_16x16x32_bf16 v[74:77], v[162:165], v[234:237], 0
	v_mfma_f32_16x16x32_bf16 v[66:69], v[180:183], v[234:237], 0
	v_mfma_f32_16x16x32_bf16 v[122:125], v[176:179], v[192:195], v[122:125]
	v_mfma_f32_16x16x32_bf16 v[114:117], v[184:187], v[192:195], v[114:117]
	v_mfma_f32_16x16x32_bf16 v[106:109], v[176:179], v[222:225], v[106:109]
	v_mfma_f32_16x16x32_bf16 v[98:101], v[184:187], v[222:225], v[98:101]
	v_mfma_f32_16x16x32_bf16 v[90:93], v[176:179], v[230:233], v[90:93]
	v_mfma_f32_16x16x32_bf16 v[82:85], v[184:187], v[230:233], v[82:85]
	v_mfma_f32_16x16x32_bf16 v[74:77], v[176:179], v[238:241], v[74:77]
	v_mfma_f32_16x16x32_bf16 v[66:69], v[184:187], v[238:241], v[66:69]
; #define PG8_STAGE(bufoff, gbase, voff) do { _Pragma("unroll") for (int _i = 0; _i < 2; ++_i) \
;         __builtin_amdgcn_global_load_lds((const unsigned*)((const char*)(gbase) + (voff)[_i]), (LAS unsigned*)(lds + (bufoff) + ldsw + _i * 8192), 16, 0, 0); } while (0)
; #define PG8_LDA(dst, b, h) do { _Pragma("unroll") for (int m = 0; m < 4; ++m) _Pragma("unroll") for (int k = 0; k < 2; ++k) dst[m][k] = *(const LAS bf16x8*)(lds + PG8_SA(b, h) + aoff + m * 2048 + k * 1024); } while (0)
; #define PG8_LDB(dst, b, h) do { _Pragma("unroll") for (int n = 0; n < 2; ++n) _Pragma("unroll") for (int k = 0; k < 2; ++k) dst[n][k] = *(const LAS bf16x8*)(lds + PG8_SB(b, h) + boff + n * 2048 + k * 1024); } while (0)
; #define PG8_MMA(ai, bj, At, Bt) do { __builtin_amdgcn_s_setprio(1); _Pragma("unroll") for (int m = 0; m < 4; ++m) _Pragma("unroll") for (int n = 0; n < 2; ++n) _Pragma("unroll") for (int k = 0; k < 2; ++k) \
;         acc[ai][bj][m][n] = __builtin_amdgcn_mfma_f32_16x16x32_bf16(Bt[n][k], At[m][k], acc[ai][bj][m][n], 0, 0, 0); __builtin_amdgcn_s_setprio(0); } while (0)
; #define PG8_WAIT_V(n) asm volatile("s_waitcnt vmcnt(" #n ")" ::: "memory")
; #define PG8_WAIT_L(n) asm volatile("s_waitcnt lgkmcnt(" #n ")" ::: "memory")
; #define PG8_BAR __builtin_amdgcn_s_barrier()
; #define PG8_SCHED __builtin_amdgcn_sched_barrier(0)
; template <class Epi>
; __device__ __forceinline__ void gemm_phase(LAS unsigned char* lds, const Sched& S, const Epi& E) {
;     ...
;             PG8_LDA(At, 0, 1); PG8_STAGE(PG8_SB(0, 0), b2, voffB); PG8_STAGE(PG8_SB(0, 1), b2 + hstepB, voffB); PG8_STAGE(PG8_SA(0, 0), a2, voffA);
;             PG8_WAIT_V(8); PG8_WAIT_L(0); PG8_BAR; PG8_MMA(1, 0, At, B0); PG8_MMA(1, 1, At, B1); PG8_BAR; PG8_SCHED;
;             PG8_LDB(B0, 1, 0); PG8_LDB(B1, 1, 1); PG8_SCHED; PG8_LDA(At, 1, 0); PG8_STAGE(PG8_SA(0, 1), a2 + hstepA, voffA);
;             PG8_WAIT_V(8); PG8_WAIT_L(0); PG8_BAR; PG8_MMA(0, 0, At, B0); PG8_MMA(0, 1, At, B1); PG8_BAR; PG8_SCHED;
.Ltskip_gateupp_0:
	s_setprio 0
	s_barrier
	s_add_i32 s49, s49, s37
	v_lshl_add_u64 v[166:167], s[26:27], 0, v[168:169]
	s_mov_b32 m0, s49
	ds_read_b128 v[188:191], v156 offset:16384
	ds_read_b128 v[192:195], v156 offset:17408
	ds_read_b128 v[196:199], v156 offset:18432
	ds_read_b128 v[222:225], v156 offset:19456
	ds_read_b128 v[226:229], v156 offset:20480
	ds_read_b128 v[230:233], v156 offset:21504
	ds_read_b128 v[234:237], v156 offset:22528
	ds_read_b128 v[238:241], v156 offset:23552
	global_load_lds_dwordx4 v[166:167], off
	s_add_i32 m0, s49, 0x2000
	s_add_u32 s94, s26, 0x80000
	v_lshl_add_u64 v[200:201], s[26:27], 0, v[134:135]
	s_addc_u32 s95, s27, 0
	s_add_i32 s49, s82, s37
	global_load_lds_dwordx4 v[200:201], off
	v_lshl_add_u64 v[242:243], s[94:95], 0, v[168:169]
	s_mov_b32 m0, s49
	v_lshl_add_u64 v[244:245], s[28:29], 0, v[132:133]
	global_load_lds_dwordx4 v[242:243], off
	v_lshl_add_u64 v[242:243], s[94:95], 0, v[134:135]
	s_add_i32 m0, s49, 0x2000
	s_nop 0
	global_load_lds_dwordx4 v[242:243], off
	v_lshl_add_u64 v[242:243], s[28:29], 0, v[130:131]
	s_mov_b32 m0, s38
	s_nop 0
	global_load_lds_dwordx4 v[242:243], off
	s_mov_b32 m0, s39
	s_nop 0
	global_load_lds_dwordx4 v[244:245], off
	s_waitcnt vmcnt(8)
	s_waitcnt lgkmcnt(0)
	s_barrier
	s_setprio 1
	s_waitcnt lgkmcnt(0)
	s_setprio 0
	s_setprio 1
	s_setprio 0
	s_barrier
	s_add_i32 s49, 0, 0x18000
	v_add_u32_e32 v157, s49, v153
	s_add_i32 s82, 0, 0x1c000
	ds_read_b128 v[140:143], v157
	ds_read_b128 v[144:147], v157 offset:1024
	ds_read_b128 v[148:151], v157 offset:2048
	ds_read_b128 v[158:161], v157 offset:3072
	v_add_u32_e32 v157, s82, v153
	ds_read_b128 v[162:165], v157
	ds_read_b128 v[176:179], v157 offset:1024
	ds_read_b128 v[180:183], v157 offset:2048
	ds_read_b128 v[184:187], v157 offset:3072
	s_add_u32 s28, s28, 0x80000
	s_addc_u32 s29, s29, 0
	s_mov_b32 m0, s58
	v_lshl_add_u64 v[246:247], s[28:29], 0, v[130:131]
	ds_read_b128 v[188:191], v156 offset:32768
	ds_read_b128 v[192:195], v156 offset:33792
	ds_read_b128 v[196:199], v156 offset:34816
	ds_read_b128 v[222:225], v156 offset:35840
	ds_read_b128 v[226:229], v156 offset:36864
	ds_read_b128 v[230:233], v156 offset:37888
	ds_read_b128 v[234:237], v156 offset:38912
	ds_read_b128 v[238:241], v156 offset:39936
	global_load_lds_dwordx4 v[246:247], off
	v_lshl_add_u64 v[246:247], s[28:29], 0, v[132:133]
	s_mov_b32 m0, s59
	s_nop 0
	global_load_lds_dwordx4 v[246:247], off
	s_waitcnt vmcnt(8)
	s_waitcnt lgkmcnt(0)
	s_barrier
	s_setprio 1
	s_waitcnt lgkmcnt(0)
	s_cmp_eq_u64 s[6:7], 0
	s_cbranch_scc1 .Ltskip_gateupp_1
	v_mfma_f32_16x16x32_bf16 v[126:129], v[140:143], v[188:191], v[126:129]
	v_mfma_f32_16x16x32_bf16 v[118:121], v[148:151], v[188:191], v[118:121]
	v_mfma_f32_16x16x32_bf16 v[110:113], v[140:143], v[196:199], v[110:113]
	v_mfma_f32_16x16x32_bf16 v[102:105], v[148:151], v[196:199], v[102:105]
	v_mfma_f32_16x16x32_bf16 v[94:97], v[140:143], v[226:229], v[94:97]
	v_mfma_f32_16x16x32_bf16 v[86:89], v[148:151], v[226:229], v[86:89]
	v_mfma_f32_16x16x32_bf16 v[78:81], v[140:143], v[234:237], v[78:81]
	v_mfma_f32_16x16x32_bf16 v[70:73], v[148:151], v[234:237], v[70:73]
	v_mfma_f32_16x16x32_bf16 v[126:129], v[144:147], v[192:195], v[126:129]
	v_mfma_f32_16x16x32_bf16 v[118:121], v[158:161], v[192:195], v[118:121]
	v_mfma_f32_16x16x32_bf16 v[110:113], v[144:147], v[222:225], v[110:113]
	v_mfma_f32_16x16x32_bf16 v[102:105], v[158:161], v[222:225], v[102:105]
	v_mfma_f32_16x16x32_bf16 v[94:97], v[144:147], v[230:233], v[94:97]
	v_mfma_f32_16x16x32_bf16 v[86:89], v[158:161], v[230:233], v[86:89]
	v_mfma_f32_16x16x32_bf16 v[78:81], v[144:147], v[238:241], v[78:81]
	v_mfma_f32_16x16x32_bf16 v[70:73], v[158:161], v[238:241], v[70:73]
	s_setprio 0
	s_setprio 1
	v_mfma_f32_16x16x32_bf16 v[122:125], v[162:165], v[188:191], v[122:125]
	v_mfma_f32_16x16x32_bf16 v[114:117], v[180:183], v[188:191], v[114:117]
	v_mfma_f32_16x16x32_bf16 v[106:109], v[162:165], v[196:199], v[106:109]
	v_mfma_f32_16x16x32_bf16 v[98:101], v[180:183], v[196:199], v[98:101]
	v_mfma_f32_16x16x32_bf16 v[90:93], v[162:165], v[226:229], v[90:93]
	v_mfma_f32_16x16x32_bf16 v[82:85], v[180:183], v[226:229], v[82:85]
	v_mfma_f32_16x16x32_bf16 v[74:77], v[162:165], v[234:237], v[74:77]
	v_mfma_f32_16x16x32_bf16 v[66:69], v[180:183], v[234:237], v[66:69]
	v_mfma_f32_16x16x32_bf16 v[122:125], v[176:179], v[192:195], v[122:125]
	v_mfma_f32_16x16x32_bf16 v[114:117], v[184:187], v[192:195], v[114:117]
	v_mfma_f32_16x16x32_bf16 v[106:109], v[176:179], v[222:225], v[106:109]
	v_mfma_f32_16x16x32_bf16 v[98:101], v[184:187], v[222:225], v[98:101]
	v_mfma_f32_16x16x32_bf16 v[90:93], v[176:179], v[230:233], v[90:93]
	v_mfma_f32_16x16x32_bf16 v[82:85], v[184:187], v[230:233], v[82:85]
	v_mfma_f32_16x16x32_bf16 v[74:77], v[176:179], v[238:241], v[74:77]
	v_mfma_f32_16x16x32_bf16 v[66:69], v[184:187], v[238:241], v[66:69]
; #define PG8_STAGE(bufoff, gbase, voff) do { _Pragma("unroll") for (int _i = 0; _i < 2; ++_i) \
;         __builtin_amdgcn_global_load_lds((const unsigned*)((const char*)(gbase) + (voff)[_i]), (LAS unsigned*)(lds + (bufoff) + ldsw + _i * 8192), 16, 0, 0); } while (0)
; #define PG8_LDA(dst, b, h) do { _Pragma("unroll") for (int m = 0; m < 4; ++m) _Pragma("unroll") for (int k = 0; k < 2; ++k) dst[m][k] = *(const LAS bf16x8*)(lds + PG8_SA(b, h) + aoff + m * 2048 + k * 1024); } while (0)
; #define PG8_LDB(dst, b, h) do { _Pragma("unroll") for (int n = 0; n < 2; ++n) _Pragma("unroll") for (int k = 0; k < 2; ++k) dst[n][k] = *(const LAS bf16x8*)(lds + PG8_SB(b, h) + boff + n * 2048 + k * 1024); } while (0)
; #define PG8_WAIT_V(n) asm volatile("s_waitcnt vmcnt(" #n ")" ::: "memory")
; #define PG8_WAIT_L(n) asm volatile("s_waitcnt lgkmcnt(" #n ")" ::: "memory")
; template <class Epi>
; __device__ __forceinline__ void gemm_phase(LAS unsigned char* lds, const Sched& S, const Epi& E) {
;     ...
;         for (int t = 0; t < nt; t += 2) {
;             const bool last = (t == nt - 2);
;             const char* a1 = cA + (size_t)(t + 1) * kstep;
;             const char* a2 = last ? nA : cA + (size_t)(t + 2) * kstep; const char* b2 = last ? nB : cB + (size_t)(t + 2) * kstep;
;             const char* a3 = a2 + kstep; const char* b3 = b2 + kstep;
;             PG8_LDB(B0, 0, 0); PG8_LDB(B1, 0, 1); PG8_SCHED; PG8_LDA(At, 0, 0); PG8_STAGE(PG8_SA(1, 1), a1 + hstepA, voffA);
;             PG8_WAIT_V(8); PG8_WAIT_L(0); PG8_BAR; PG8_MMA(0, 0, At, B0); PG8_MMA(0, 1, At, B1); PG8_BAR; PG8_SCHED;
;             PG8_LDA(At, 0, 1); PG8_STAGE(PG8_SB(0, 0), b2, voffB); PG8_STAGE(PG8_SB(0, 1), b2 + hstepB, voffB); PG8_STAGE(PG8_SA(0, 0), a2, voffA);
;             PG8_WAIT_V(8); PG8_WAIT_L(0); PG8_BAR; PG8_MMA(1, 0, At, B0); PG8_MMA(1, 1, At, B1); PG8_BAR; PG8_SCHED;
;             PG8_LDB(B0, 1, 0); PG8_LDB(B1, 1, 1); PG8_SCHED; PG8_LDA(At, 1, 0); PG8_STAGE(PG8_SA(0, 1), a2 + hstepA, voffA);
;             PG8_WAIT_V(8); PG8_WAIT_L(0); PG8_BAR; PG8_MMA(0, 0, At, B0); PG8_MMA(0, 1, At, B1); PG8_BAR; PG8_SCHED;
;             PG8_LDA(At, 1, 1); PG8_STAGE(PG8_SB(1, 0), b3, voffB); PG8_STAGE(PG8_SB(1, 1), b3 + hstepB, voffB); PG8_STAGE(PG8_SA(1, 0), a3, voffA);
;             PG8_WAIT_V(8); PG8_WAIT_L(0); PG8_BAR; PG8_MMA(1, 0, At, B0); PG8_MMA(1, 1, At, B1); PG8_BAR; PG8_SCHED;
;         }
.Ltskip_gateupp_1:
	s_setprio 0
	s_barrier
	s_add_i32 s28, s49, s37
	v_lshl_add_u64 v[166:167], v[166:167], 0, s[0:1]
	s_mov_b32 m0, s28
	ds_read_b128 v[188:191], v156 offset:49152
	ds_read_b128 v[192:195], v156 offset:50176
	ds_read_b128 v[196:199], v156 offset:51200
	ds_read_b128 v[222:225], v156 offset:52224
	ds_read_b128 v[226:229], v156 offset:53248
	ds_read_b128 v[230:233], v156 offset:54272
	ds_read_b128 v[234:237], v156 offset:55296
	ds_read_b128 v[238:241], v156 offset:56320
	global_load_lds_dwordx4 v[166:167], off
	s_add_i32 m0, s28, 0x2000
	s_add_u32 s26, s26, 0x80080
	v_lshl_add_u64 v[166:167], v[200:201], 0, s[0:1]
	s_addc_u32 s27, s27, 0
	s_add_i32 s28, s82, s37
	global_load_lds_dwordx4 v[166:167], off
	v_lshl_add_u64 v[166:167], s[26:27], 0, v[168:169]
	s_mov_b32 m0, s28
	s_nop 0
	global_load_lds_dwordx4 v[166:167], off
	v_lshl_add_u64 v[166:167], s[26:27], 0, v[134:135]
	s_add_i32 m0, s28, 0x2000
	s_nop 0
	global_load_lds_dwordx4 v[166:167], off
	v_lshl_add_u64 v[166:167], v[242:243], 0, s[0:1]
	s_mov_b32 m0, s64
	s_nop 0
	global_load_lds_dwordx4 v[166:167], off
	v_lshl_add_u64 v[166:167], v[244:245], 0, s[0:1]
	s_mov_b32 m0, s65
	s_nop 0
	global_load_lds_dwordx4 v[166:167], off
	s_waitcnt vmcnt(8)
	s_waitcnt lgkmcnt(0)
	s_barrier
	s_setprio 1
	s_waitcnt lgkmcnt(0)
	s_setprio 0
	s_setprio 1
	s_setprio 0
	s_barrier
	s_add_i32 s69, s69, 2
	s_add_u32 s24, s24, 0x100
	s_addc_u32 s25, s25, 0
	s_add_u32 s9, s9, 0x100
	s_addc_u32 s11, s11, 0
	s_cmp_gt_u32 s69, 29
	s_cbranch_scc1 .Lpeel_exit_gateup
.Ltail_loop_gateup:
	s_add_u32 s26, s24, 0xfff80080
	s_addc_u32 s27, s25, -1
	s_add_i32 s49, 0, 0x10000
	s_cmp_eq_u32 s69, 28
	s_cselect_b32 s29, s19, s27
	s_cselect_b32 s28, s18, s26
	v_add_u32_e32 v157, s49, v153
	s_cselect_b32 s27, s23, s11
	s_cselect_b32 s26, s22, s9
	s_add_i32 s82, 0, 0x14000
	ds_read_b128 v[140:143], v157
	ds_read_b128 v[144:147], v157 offset:1024
	ds_read_b128 v[148:151], v157 offset:2048
	ds_read_b128 v[158:161], v157 offset:3072
	v_add_u32_e32 v157, s82, v153
	ds_read_b128 v[162:165], v157
	ds_read_b128 v[176:179], v157 offset:1024
	ds_read_b128 v[180:183], v157 offset:2048
	ds_read_b128 v[184:187], v157 offset:3072
	v_lshl_add_u64 v[166:167], s[24:25], 0, v[136:137]
	s_add_i32 m0, s38, 0xc000
	ds_read_b128 v[188:191], v156
	ds_read_b128 v[192:195], v156 offset:1024
	ds_read_b128 v[196:199], v156 offset:2048
	ds_read_b128 v[222:225], v156 offset:3072
	ds_read_b128 v[226:229], v156 offset:4096
	ds_read_b128 v[230:233], v156 offset:5120
	ds_read_b128 v[234:237], v156 offset:6144
	ds_read_b128 v[238:241], v156 offset:7168
	global_load_lds_dwordx4 v[166:167], off
	v_lshl_add_u64 v[166:167], s[24:25], 0, v[138:139]
	s_add_i32 m0, s38, 0xe000
	s_nop 0
	global_load_lds_dwordx4 v[166:167], off
	s_waitcnt vmcnt(8)
	s_waitcnt lgkmcnt(0)
	s_barrier
	s_setprio 1
	s_waitcnt lgkmcnt(0)
	s_cmp_eq_u64 s[6:7], 0
	s_cbranch_scc1 .Ltskip_gateupl_0
	v_mfma_f32_16x16x32_bf16 v[126:129], v[140:143], v[188:191], v[126:129]
	v_mfma_f32_16x16x32_bf16 v[118:121], v[148:151], v[188:191], v[118:121]
	v_mfma_f32_16x16x32_bf16 v[110:113], v[140:143], v[196:199], v[110:113]
	v_mfma_f32_16x16x32_bf16 v[102:105], v[148:151], v[196:199], v[102:105]
	v_mfma_f32_16x16x32_bf16 v[94:97], v[140:143], v[226:229], v[94:97]
	v_mfma_f32_16x16x32_bf16 v[86:89], v[148:151], v[226:229], v[86:89]
	v_mfma_f32_16x16x32_bf16 v[78:81], v[140:143], v[234:237], v[78:81]
	v_mfma_f32_16x16x32_bf16 v[70:73], v[148:151], v[234:237], v[70:73]
	v_mfma_f32_16x16x32_bf16 v[126:129], v[144:147], v[192:195], v[126:129]
	v_mfma_f32_16x16x32_bf16 v[118:121], v[158:161], v[192:195], v[118:121]
	v_mfma_f32_16x16x32_bf16 v[110:113], v[144:147], v[222:225], v[110:113]
	v_mfma_f32_16x16x32_bf16 v[102:105], v[158:161], v[222:225], v[102:105]
	v_mfma_f32_16x16x32_bf16 v[94:97], v[144:147], v[230:233], v[94:97]
	v_mfma_f32_16x16x32_bf16 v[86:89], v[158:161], v[230:233], v[86:89]
	v_mfma_f32_16x16x32_bf16 v[78:81], v[144:147], v[238:241], v[78:81]
	v_mfma_f32_16x16x32_bf16 v[70:73], v[158:161], v[238:241], v[70:73]
	s_setprio 0
	s_setprio 1
	v_mfma_f32_16x16x32_bf16 v[122:125], v[162:165], v[188:191], v[122:125]
	v_mfma_f32_16x16x32_bf16 v[114:117], v[180:183], v[188:191], v[114:117]
	v_mfma_f32_16x16x32_bf16 v[106:109], v[162:165], v[196:199], v[106:109]
	v_mfma_f32_16x16x32_bf16 v[98:101], v[180:183], v[196:199], v[98:101]
	v_mfma_f32_16x16x32_bf16 v[90:93], v[162:165], v[226:229], v[90:93]
	v_mfma_f32_16x16x32_bf16 v[82:85], v[180:183], v[226:229], v[82:85]
	v_mfma_f32_16x16x32_bf16 v[74:77], v[162:165], v[234:237], v[74:77]
	v_mfma_f32_16x16x32_bf16 v[66:69], v[180:183], v[234:237], v[66:69]
	v_mfma_f32_16x16x32_bf16 v[122:125], v[176:179], v[192:195], v[122:125]
	v_mfma_f32_16x16x32_bf16 v[114:117], v[184:187], v[192:195], v[114:117]
	v_mfma_f32_16x16x32_bf16 v[106:109], v[176:179], v[222:225], v[106:109]
	v_mfma_f32_16x16x32_bf16 v[98:101], v[184:187], v[222:225], v[98:101]
	v_mfma_f32_16x16x32_bf16 v[90:93], v[176:179], v[230:233], v[90:93]
	v_mfma_f32_16x16x32_bf16 v[82:85], v[184:187], v[230:233], v[82:85]
	v_mfma_f32_16x16x32_bf16 v[74:77], v[176:179], v[238:241], v[74:77]
	v_mfma_f32_16x16x32_bf16 v[66:69], v[184:187], v[238:241], v[66:69]

; #define PG8_STAGE(bufoff, gbase, voff) do { _Pragma("unroll") for (int _i = 0; _i < 2; ++_i) \
;         __builtin_amdgcn_global_load_lds((const unsigned*)((const char*)(gbase) + (voff)[_i]), (LAS unsigned*)(lds + (bufoff) + ldsw + _i * 8192), 16, 0, 0); } while (0)
; #define PG8_LDA(dst, b, h) do { _Pragma("unroll") for (int m = 0; m < 4; ++m) _Pragma("unroll") for (int k = 0; k < 2; ++k) dst[m][k] = *(const LAS bf16x8*)(lds + PG8_SA(b, h) + aoff + m * 2048 + k * 1024); } while (0)
; #define PG8_MMA(ai, bj, At, Bt) do { __builtin_amdgcn_s_setprio(1); _Pragma("unroll") for (int m = 0; m < 4; ++m) _Pragma("unroll") for (int n = 0; n < 2; ++n) _Pragma("unroll") for (int k = 0; k < 2; ++k) \
;         acc[ai][bj][m][n] = __builtin_amdgcn_mfma_f32_16x16x32_bf16(Bt[n][k], At[m][k], acc[ai][bj][m][n], 0, 0, 0); __builtin_amdgcn_s_setprio(0); } while (0)
; #define PG8_WAIT_V(n) asm volatile("s_waitcnt vmcnt(" #n ")" ::: "memory")
; #define PG8_WAIT_L(n) asm volatile("s_waitcnt lgkmcnt(" #n ")" ::: "memory")
; #define PG8_BAR __builtin_amdgcn_s_barrier()
; #define PG8_SCHED __builtin_amdgcn_sched_barrier(0)
; template <class Epi>
; __device__ __forceinline__ void gemm_phase(LAS unsigned char* lds, const Sched& S, const Epi& E) {
;     ...
;             PG8_LDA(At, 1, 1); PG8_STAGE(PG8_SB(1, 0), b3, voffB); PG8_STAGE(PG8_SB(1, 1), b3 + hstepB, voffB); PG8_STAGE(PG8_SA(1, 0), a3, voffA);
;             PG8_WAIT_V(8); PG8_WAIT_L(0); PG8_BAR; PG8_MMA(1, 0, At, B0); PG8_MMA(1, 1, At, B1); PG8_BAR; PG8_SCHED;
;         }
.Ltskip_gateupl_1:
	s_setprio 0
	s_barrier
	s_add_i32 s28, s49, s37
	v_lshl_add_u64 v[166:167], v[166:167], 0, s[0:1]
	s_mov_b32 m0, s28
	ds_read_b128 v[188:191], v156 offset:49152
	ds_read_b128 v[192:195], v156 offset:50176
	ds_read_b128 v[196:199], v156 offset:51200
	ds_read_b128 v[222:225], v156 offset:52224
	ds_read_b128 v[226:229], v156 offset:53248
	ds_read_b128 v[230:233], v156 offset:54272
	ds_read_b128 v[234:237], v156 offset:55296
	ds_read_b128 v[238:241], v156 offset:56320
	global_load_lds_dwordx4 v[166:167], off
	s_add_i32 m0, s28, 0x2000
	s_add_u32 s26, s26, 0x80080
	v_lshl_add_u64 v[166:167], v[200:201], 0, s[0:1]
	s_addc_u32 s27, s27, 0
	s_add_i32 s28, s82, s37
	global_load_lds_dwordx4 v[166:167], off
	v_lshl_add_u64 v[166:167], s[26:27], 0, v[168:169]
	s_mov_b32 m0, s28
	s_nop 0
	global_load_lds_dwordx4 v[166:167], off
	v_lshl_add_u64 v[166:167], s[26:27], 0, v[134:135]
	s_add_i32 m0, s28, 0x2000
	s_nop 0
	global_load_lds_dwordx4 v[166:167], off
	v_lshl_add_u64 v[166:167], v[242:243], 0, s[0:1]
	s_mov_b32 m0, s64
	s_nop 0
	global_load_lds_dwordx4 v[166:167], off
	v_lshl_add_u64 v[166:167], v[244:245], 0, s[0:1]
	s_mov_b32 m0, s65
	s_nop 0
	global_load_lds_dwordx4 v[166:167], off
	s_waitcnt vmcnt(8)
	s_waitcnt lgkmcnt(0)
	s_barrier
	s_setprio 1
	s_waitcnt lgkmcnt(0)
	s_setprio 0
	s_setprio 1
	s_setprio 0
	s_barrier
	s_add_i32 s69, s69, 2
	s_add_u32 s24, s24, 0x100
	s_addc_u32 s25, s25, 0
	s_add_u32 s9, s9, 0x100
	s_addc_u32 s11, s11, 0
	s_cmp_gt_u32 s69, 29
	s_cbranch_scc0 .Ltail_loop_gateup
